# parameter variant: GEMM barrier behind the first 4 MFMAs after the short (2-piece) load phase and behind the first 2 after the long (6-piece) one
# speedup vs baseline: 1.0055x; 1.0015x over previous
.LBB0_168:
	s_add_u32 s46, s66, 0xfff80080
	s_addc_u32 s47, s67, -1
	s_add_i32 s62, 0, 0x10000
	s_cmp_eq_u32 s82, 28
	s_cselect_b32 s69, s17, s47
	s_cselect_b32 s68, s65, s46
	v_add_u32_e32 v143, s62, v140
	s_cselect_b32 s61, s13, s81
	s_cselect_b32 s60, s79, s80
	s_add_i32 s63, 0, 0x14000
	ds_read_b128 v[144:147], v143
	ds_read_b128 v[148:151], v143 offset:1024
	ds_read_b128 v[152:155], v143 offset:2048
	ds_read_b128 v[156:159], v143 offset:3072
	v_add_u32_e32 v143, s63, v140
	ds_read_b128 v[160:163], v143
	ds_read_b128 v[178:181], v143 offset:1024
	ds_read_b128 v[182:185], v143 offset:2048
	ds_read_b128 v[186:189], v143 offset:3072
	v_lshl_add_u64 v[164:165], s[66:67], 0, v[136:137]
	s_add_i32 m0, s19, 0xc000
	ds_read_b128 v[206:209], v142
	ds_read_b128 v[210:213], v142 offset:1024
	ds_read_b128 v[214:217], v142 offset:2048
	ds_read_b128 v[218:221], v142 offset:3072
	ds_read_b128 v[222:225], v142 offset:4096
	ds_read_b128 v[226:229], v142 offset:5120
	ds_read_b128 v[230:233], v142 offset:6144
	ds_read_b128 v[234:237], v142 offset:7168
	global_load_lds_dwordx4 v[164:165], off
	v_lshl_add_u64 v[164:165], s[66:67], 0, v[138:139]
	s_add_i32 m0, s19, 0xe000
	s_nop 0
	global_load_lds_dwordx4 v[164:165], off
	s_waitcnt vmcnt(8)
	s_waitcnt lgkmcnt(0)
	s_setprio 1
	s_waitcnt lgkmcnt(0)
	v_mfma_f32_16x16x32_bf16 v[126:129], v[144:147], v[206:209], v[126:129]
	v_mfma_f32_16x16x32_bf16 v[122:125], v[152:155], v[206:209], v[122:125]
	v_mfma_f32_16x16x32_bf16 v[118:121], v[144:147], v[214:217], v[118:121]
	v_mfma_f32_16x16x32_bf16 v[114:117], v[152:155], v[214:217], v[114:117]
	s_barrier
	v_mfma_f32_16x16x32_bf16 v[102:105], v[144:147], v[222:225], v[102:105]
	v_mfma_f32_16x16x32_bf16 v[98:101], v[152:155], v[222:225], v[98:101]
	v_mfma_f32_16x16x32_bf16 v[86:89], v[144:147], v[230:233], v[86:89]
	v_mfma_f32_16x16x32_bf16 v[82:85], v[152:155], v[230:233], v[82:85]
	v_mfma_f32_16x16x32_bf16 v[126:129], v[148:151], v[210:213], v[126:129]
	v_mfma_f32_16x16x32_bf16 v[122:125], v[156:159], v[210:213], v[122:125]
	v_mfma_f32_16x16x32_bf16 v[118:121], v[148:151], v[218:221], v[118:121]
	v_mfma_f32_16x16x32_bf16 v[114:117], v[156:159], v[218:221], v[114:117]
	v_mfma_f32_16x16x32_bf16 v[102:105], v[148:151], v[226:229], v[102:105]
	v_mfma_f32_16x16x32_bf16 v[98:101], v[156:159], v[226:229], v[98:101]
	v_mfma_f32_16x16x32_bf16 v[86:89], v[148:151], v[234:237], v[86:89]
	v_mfma_f32_16x16x32_bf16 v[82:85], v[156:159], v[234:237], v[82:85]
	v_mfma_f32_16x16x32_bf16 v[110:113], v[160:163], v[206:209], v[110:113]
	v_mfma_f32_16x16x32_bf16 v[106:109], v[182:185], v[206:209], v[106:109]
	v_mfma_f32_16x16x32_bf16 v[94:97], v[160:163], v[214:217], v[94:97]
	v_mfma_f32_16x16x32_bf16 v[90:93], v[182:185], v[214:217], v[90:93]
	v_mfma_f32_16x16x32_bf16 v[78:81], v[160:163], v[222:225], v[78:81]
	v_mfma_f32_16x16x32_bf16 v[74:77], v[182:185], v[222:225], v[74:77]
	v_mfma_f32_16x16x32_bf16 v[70:73], v[160:163], v[230:233], v[70:73]
	v_mfma_f32_16x16x32_bf16 v[66:69], v[182:185], v[230:233], v[66:69]
	v_mfma_f32_16x16x32_bf16 v[110:113], v[178:181], v[210:213], v[110:113]
	v_mfma_f32_16x16x32_bf16 v[106:109], v[186:189], v[210:213], v[106:109]
	v_mfma_f32_16x16x32_bf16 v[94:97], v[178:181], v[218:221], v[94:97]
	v_mfma_f32_16x16x32_bf16 v[90:93], v[186:189], v[218:221], v[90:93]
	v_mfma_f32_16x16x32_bf16 v[78:81], v[178:181], v[226:229], v[78:81]
	v_mfma_f32_16x16x32_bf16 v[74:77], v[186:189], v[226:229], v[74:77]
	v_mfma_f32_16x16x32_bf16 v[70:73], v[178:181], v[234:237], v[70:73]
	v_mfma_f32_16x16x32_bf16 v[66:69], v[186:189], v[234:237], v[66:69]
	s_barrier
	s_setprio 0
	s_add_i32 s46, s62, s71
	v_lshl_add_u64 v[164:165], s[60:61], 0, v[166:167]
	s_mov_b32 m0, s46
	ds_read_b128 v[206:209], v142 offset:16384
	ds_read_b128 v[210:213], v142 offset:17408
	ds_read_b128 v[214:217], v142 offset:18432
	ds_read_b128 v[218:221], v142 offset:19456
	ds_read_b128 v[222:225], v142 offset:20480
	ds_read_b128 v[226:229], v142 offset:21504
	ds_read_b128 v[230:233], v142 offset:22528
	ds_read_b128 v[234:237], v142 offset:23552
	global_load_lds_dwordx4 v[164:165], off
	s_add_i32 m0, s46, 0x2000
	s_add_u32 s46, s60, 0x80000
	v_lshl_add_u64 v[242:243], s[60:61], 0, v[130:131]
	s_addc_u32 s47, s61, 0
	s_add_i32 s62, s63, s71
	global_load_lds_dwordx4 v[242:243], off
	v_lshl_add_u64 v[244:245], s[46:47], 0, v[166:167]
	s_mov_b32 m0, s62
	v_lshl_add_u64 v[246:247], s[68:69], 0, v[132:133]
	global_load_lds_dwordx4 v[244:245], off
	v_lshl_add_u64 v[244:245], s[46:47], 0, v[130:131]
	s_add_i32 m0, s62, 0x2000
	s_nop 0
	global_load_lds_dwordx4 v[244:245], off
	v_lshl_add_u64 v[244:245], s[68:69], 0, v[134:135]
	s_mov_b32 m0, s19
	s_nop 0
	global_load_lds_dwordx4 v[244:245], off
	s_mov_b32 m0, s73
	s_nop 0
	global_load_lds_dwordx4 v[246:247], off
	s_waitcnt vmcnt(8)
	s_waitcnt lgkmcnt(0)
	s_setprio 1
	s_waitcnt lgkmcnt(0)
	v_mfma_f32_16x16x32_bf16 v[62:65], v[144:147], v[206:209], v[62:65]
	v_mfma_f32_16x16x32_bf16 v[58:61], v[152:155], v[206:209], v[58:61]
	s_barrier
	v_mfma_f32_16x16x32_bf16 v[54:57], v[144:147], v[214:217], v[54:57]
	v_mfma_f32_16x16x32_bf16 v[50:53], v[152:155], v[214:217], v[50:53]
	v_mfma_f32_16x16x32_bf16 v[38:41], v[144:147], v[222:225], v[38:41]
	v_mfma_f32_16x16x32_bf16 v[34:37], v[152:155], v[222:225], v[34:37]
	v_mfma_f32_16x16x32_bf16 v[22:25], v[144:147], v[230:233], v[22:25]
	v_mfma_f32_16x16x32_bf16 v[18:21], v[152:155], v[230:233], v[18:21]
	v_mfma_f32_16x16x32_bf16 v[62:65], v[148:151], v[210:213], v[62:65]
	v_mfma_f32_16x16x32_bf16 v[58:61], v[156:159], v[210:213], v[58:61]
	v_mfma_f32_16x16x32_bf16 v[54:57], v[148:151], v[218:221], v[54:57]
	v_mfma_f32_16x16x32_bf16 v[50:53], v[156:159], v[218:221], v[50:53]
	v_mfma_f32_16x16x32_bf16 v[38:41], v[148:151], v[226:229], v[38:41]
	v_mfma_f32_16x16x32_bf16 v[34:37], v[156:159], v[226:229], v[34:37]
	v_mfma_f32_16x16x32_bf16 v[22:25], v[148:151], v[234:237], v[22:25]
	v_mfma_f32_16x16x32_bf16 v[18:21], v[156:159], v[234:237], v[18:21]
	v_mfma_f32_16x16x32_bf16 v[46:49], v[160:163], v[206:209], v[46:49]
	v_mfma_f32_16x16x32_bf16 v[42:45], v[182:185], v[206:209], v[42:45]
	v_mfma_f32_16x16x32_bf16 v[30:33], v[160:163], v[214:217], v[30:33]
	v_mfma_f32_16x16x32_bf16 v[26:29], v[182:185], v[214:217], v[26:29]
	v_mfma_f32_16x16x32_bf16 v[14:17], v[160:163], v[222:225], v[14:17]
	v_mfma_f32_16x16x32_bf16 v[10:13], v[182:185], v[222:225], v[10:13]
	v_mfma_f32_16x16x32_bf16 v[6:9], v[160:163], v[230:233], v[6:9]
	v_mfma_f32_16x16x32_bf16 v[2:5], v[182:185], v[230:233], v[2:5]
	v_mfma_f32_16x16x32_bf16 v[46:49], v[178:181], v[210:213], v[46:49]
	v_mfma_f32_16x16x32_bf16 v[42:45], v[186:189], v[210:213], v[42:45]
	v_mfma_f32_16x16x32_bf16 v[30:33], v[178:181], v[218:221], v[30:33]
	v_mfma_f32_16x16x32_bf16 v[26:29], v[186:189], v[218:221], v[26:29]
	v_mfma_f32_16x16x32_bf16 v[14:17], v[178:181], v[226:229], v[14:17]
	v_mfma_f32_16x16x32_bf16 v[10:13], v[186:189], v[226:229], v[10:13]
	v_mfma_f32_16x16x32_bf16 v[6:9], v[178:181], v[234:237], v[6:9]
	v_mfma_f32_16x16x32_bf16 v[2:5], v[186:189], v[234:237], v[2:5]
	s_barrier
	s_setprio 0
	s_add_i32 s62, 0, 0x18000
	v_add_u32_e32 v143, s62, v140
	s_add_i32 s63, 0, 0x1c000
	ds_read_b128 v[144:147], v143
	ds_read_b128 v[148:151], v143 offset:1024
	ds_read_b128 v[152:155], v143 offset:2048
	ds_read_b128 v[156:159], v143 offset:3072
	v_add_u32_e32 v143, s63, v140
	ds_read_b128 v[160:163], v143
	ds_read_b128 v[178:181], v143 offset:1024
	ds_read_b128 v[182:185], v143 offset:2048
	ds_read_b128 v[186:189], v143 offset:3072
	s_add_u32 s46, s68, 0x80000
	s_addc_u32 s47, s69, 0
	s_mov_b32 m0, s74
	v_lshl_add_u64 v[248:249], s[46:47], 0, v[134:135]
	ds_read_b128 v[206:209], v142 offset:32768
	ds_read_b128 v[210:213], v142 offset:33792
	ds_read_b128 v[214:217], v142 offset:34816
	ds_read_b128 v[218:221], v142 offset:35840
	ds_read_b128 v[222:225], v142 offset:36864
	ds_read_b128 v[226:229], v142 offset:37888
	ds_read_b128 v[230:233], v142 offset:38912
	ds_read_b128 v[234:237], v142 offset:39936
	global_load_lds_dwordx4 v[248:249], off
	v_lshl_add_u64 v[248:249], s[46:47], 0, v[132:133]
	s_mov_b32 m0, s75
	s_nop 0
	global_load_lds_dwordx4 v[248:249], off
	s_waitcnt vmcnt(8)
	s_waitcnt lgkmcnt(0)
	s_setprio 1
	s_waitcnt lgkmcnt(0)
	v_mfma_f32_16x16x32_bf16 v[126:129], v[144:147], v[206:209], v[126:129]
	v_mfma_f32_16x16x32_bf16 v[122:125], v[152:155], v[206:209], v[122:125]
	v_mfma_f32_16x16x32_bf16 v[118:121], v[144:147], v[214:217], v[118:121]
	v_mfma_f32_16x16x32_bf16 v[114:117], v[152:155], v[214:217], v[114:117]
	s_barrier
	v_mfma_f32_16x16x32_bf16 v[102:105], v[144:147], v[222:225], v[102:105]
	v_mfma_f32_16x16x32_bf16 v[98:101], v[152:155], v[222:225], v[98:101]
	v_mfma_f32_16x16x32_bf16 v[86:89], v[144:147], v[230:233], v[86:89]
	v_mfma_f32_16x16x32_bf16 v[82:85], v[152:155], v[230:233], v[82:85]
	v_mfma_f32_16x16x32_bf16 v[126:129], v[148:151], v[210:213], v[126:129]
	v_mfma_f32_16x16x32_bf16 v[122:125], v[156:159], v[210:213], v[122:125]
	v_mfma_f32_16x16x32_bf16 v[118:121], v[148:151], v[218:221], v[118:121]
	v_mfma_f32_16x16x32_bf16 v[114:117], v[156:159], v[218:221], v[114:117]
	v_mfma_f32_16x16x32_bf16 v[102:105], v[148:151], v[226:229], v[102:105]
	v_mfma_f32_16x16x32_bf16 v[98:101], v[156:159], v[226:229], v[98:101]
	v_mfma_f32_16x16x32_bf16 v[86:89], v[148:151], v[234:237], v[86:89]
	v_mfma_f32_16x16x32_bf16 v[82:85], v[156:159], v[234:237], v[82:85]
	v_mfma_f32_16x16x32_bf16 v[110:113], v[160:163], v[206:209], v[110:113]
	v_mfma_f32_16x16x32_bf16 v[106:109], v[182:185], v[206:209], v[106:109]
	v_mfma_f32_16x16x32_bf16 v[94:97], v[160:163], v[214:217], v[94:97]
	v_mfma_f32_16x16x32_bf16 v[90:93], v[182:185], v[214:217], v[90:93]
	v_mfma_f32_16x16x32_bf16 v[78:81], v[160:163], v[222:225], v[78:81]
	v_mfma_f32_16x16x32_bf16 v[74:77], v[182:185], v[222:225], v[74:77]
	v_mfma_f32_16x16x32_bf16 v[70:73], v[160:163], v[230:233], v[70:73]
	v_mfma_f32_16x16x32_bf16 v[66:69], v[182:185], v[230:233], v[66:69]
	v_mfma_f32_16x16x32_bf16 v[110:113], v[178:181], v[210:213], v[110:113]
	v_mfma_f32_16x16x32_bf16 v[106:109], v[186:189], v[210:213], v[106:109]
	v_mfma_f32_16x16x32_bf16 v[94:97], v[178:181], v[218:221], v[94:97]
	v_mfma_f32_16x16x32_bf16 v[90:93], v[186:189], v[218:221], v[90:93]
	v_mfma_f32_16x16x32_bf16 v[78:81], v[178:181], v[226:229], v[78:81]
	v_mfma_f32_16x16x32_bf16 v[74:77], v[186:189], v[226:229], v[74:77]
	v_mfma_f32_16x16x32_bf16 v[70:73], v[178:181], v[234:237], v[70:73]
	v_mfma_f32_16x16x32_bf16 v[66:69], v[186:189], v[234:237], v[66:69]
	s_barrier
	s_setprio 0
	s_add_i32 s46, s62, s71
	v_lshl_add_u64 v[164:165], v[164:165], 0, s[42:43]
	s_mov_b32 m0, s46
	ds_read_b128 v[206:209], v142 offset:49152
	ds_read_b128 v[210:213], v142 offset:50176
	ds_read_b128 v[214:217], v142 offset:51200
	ds_read_b128 v[218:221], v142 offset:52224
	ds_read_b128 v[222:225], v142 offset:53248
	ds_read_b128 v[226:229], v142 offset:54272
	ds_read_b128 v[230:233], v142 offset:55296
	ds_read_b128 v[234:237], v142 offset:56320
	global_load_lds_dwordx4 v[164:165], off
	s_add_i32 m0, s46, 0x2000
	s_add_u32 s46, s60, 0x80080
	v_lshl_add_u64 v[164:165], v[242:243], 0, s[42:43]
	s_addc_u32 s47, s61, 0
	s_add_i32 s60, s63, s71
	global_load_lds_dwordx4 v[164:165], off
	v_lshl_add_u64 v[164:165], s[46:47], 0, v[166:167]
	s_mov_b32 m0, s60
	s_nop 0
	global_load_lds_dwordx4 v[164:165], off
	v_lshl_add_u64 v[164:165], s[46:47], 0, v[130:131]
	s_add_i32 m0, s60, 0x2000
	s_nop 0
	global_load_lds_dwordx4 v[164:165], off
	v_lshl_add_u64 v[164:165], v[244:245], 0, s[42:43]
	s_mov_b32 m0, s76
	s_nop 0
	global_load_lds_dwordx4 v[164:165], off
	v_lshl_add_u64 v[164:165], v[246:247], 0, s[42:43]
	s_mov_b32 m0, s77
	s_nop 0
	global_load_lds_dwordx4 v[164:165], off
	s_waitcnt vmcnt(8)
	s_waitcnt lgkmcnt(0)
	s_setprio 1
	s_waitcnt lgkmcnt(0)
	v_mfma_f32_16x16x32_bf16 v[62:65], v[144:147], v[206:209], v[62:65]
	v_mfma_f32_16x16x32_bf16 v[58:61], v[152:155], v[206:209], v[58:61]
	s_barrier
	v_mfma_f32_16x16x32_bf16 v[54:57], v[144:147], v[214:217], v[54:57]
	v_mfma_f32_16x16x32_bf16 v[50:53], v[152:155], v[214:217], v[50:53]
	v_mfma_f32_16x16x32_bf16 v[38:41], v[144:147], v[222:225], v[38:41]
	v_mfma_f32_16x16x32_bf16 v[34:37], v[152:155], v[222:225], v[34:37]
	v_mfma_f32_16x16x32_bf16 v[22:25], v[144:147], v[230:233], v[22:25]
	v_mfma_f32_16x16x32_bf16 v[18:21], v[152:155], v[230:233], v[18:21]
	v_mfma_f32_16x16x32_bf16 v[62:65], v[148:151], v[210:213], v[62:65]
	v_mfma_f32_16x16x32_bf16 v[58:61], v[156:159], v[210:213], v[58:61]
	v_mfma_f32_16x16x32_bf16 v[54:57], v[148:151], v[218:221], v[54:57]
	v_mfma_f32_16x16x32_bf16 v[50:53], v[156:159], v[218:221], v[50:53]
	v_mfma_f32_16x16x32_bf16 v[38:41], v[148:151], v[226:229], v[38:41]
	v_mfma_f32_16x16x32_bf16 v[34:37], v[156:159], v[226:229], v[34:37]
	v_mfma_f32_16x16x32_bf16 v[22:25], v[148:151], v[234:237], v[22:25]
	v_mfma_f32_16x16x32_bf16 v[18:21], v[156:159], v[234:237], v[18:21]
	v_mfma_f32_16x16x32_bf16 v[46:49], v[160:163], v[206:209], v[46:49]
	v_mfma_f32_16x16x32_bf16 v[42:45], v[182:185], v[206:209], v[42:45]
	v_mfma_f32_16x16x32_bf16 v[30:33], v[160:163], v[214:217], v[30:33]
	v_mfma_f32_16x16x32_bf16 v[26:29], v[182:185], v[214:217], v[26:29]
	v_mfma_f32_16x16x32_bf16 v[14:17], v[160:163], v[222:225], v[14:17]
	v_mfma_f32_16x16x32_bf16 v[10:13], v[182:185], v[222:225], v[10:13]
	v_mfma_f32_16x16x32_bf16 v[6:9], v[160:163], v[230:233], v[6:9]
	v_mfma_f32_16x16x32_bf16 v[2:5], v[182:185], v[230:233], v[2:5]
	v_mfma_f32_16x16x32_bf16 v[46:49], v[178:181], v[210:213], v[46:49]
	v_mfma_f32_16x16x32_bf16 v[42:45], v[186:189], v[210:213], v[42:45]
	v_mfma_f32_16x16x32_bf16 v[30:33], v[178:181], v[218:221], v[30:33]
	v_mfma_f32_16x16x32_bf16 v[26:29], v[186:189], v[218:221], v[26:29]
	v_mfma_f32_16x16x32_bf16 v[14:17], v[178:181], v[226:229], v[14:17]
	v_mfma_f32_16x16x32_bf16 v[10:13], v[186:189], v[226:229], v[10:13]
	v_mfma_f32_16x16x32_bf16 v[6:9], v[178:181], v[234:237], v[6:9]
	v_mfma_f32_16x16x32_bf16 v[2:5], v[186:189], v[234:237], v[2:5]
	s_barrier
	s_setprio 0
	s_add_i32 s82, s82, 2
	s_add_u32 s66, s66, 0x100
	s_addc_u32 s67, s67, 0
	s_add_u32 s80, s80, 0x100
	s_addc_u32 s81, s81, 0
	s_cmp_gt_u32 s82, 29
	s_cbranch_scc0 .LBB0_168
	s_and_b64 vcc, exec, s[10:11]
	s_cbranch_vccz .LBB0_171
	s_barrier

.LBB0_426:
	s_add_u32 s46, s66, 0xfffe0080
	s_addc_u32 s47, s67, -1
	s_add_i32 s62, 0, 0x10000
	s_cmp_eq_u32 s84, 4
	s_cselect_b32 s69, s19, s47
	s_cselect_b32 s68, s80, s46
	v_add_u32_e32 v143, s62, v140
	s_cselect_b32 s61, s17, s83
	s_cselect_b32 s60, s81, s82
	s_add_i32 s63, 0, 0x14000
	ds_read_b128 v[144:147], v143
	ds_read_b128 v[148:151], v143 offset:1024
	ds_read_b128 v[152:155], v143 offset:2048
	ds_read_b128 v[156:159], v143 offset:3072
	v_add_u32_e32 v143, s63, v140
	ds_read_b128 v[160:163], v143
	ds_read_b128 v[178:181], v143 offset:1024
	ds_read_b128 v[182:185], v143 offset:2048
	ds_read_b128 v[186:189], v143 offset:3072
	v_lshl_add_u64 v[164:165], s[66:67], 0, v[136:137]
	s_add_i32 m0, s11, 0xc000
	ds_read_b128 v[206:209], v142
	ds_read_b128 v[210:213], v142 offset:1024
	ds_read_b128 v[214:217], v142 offset:2048
	ds_read_b128 v[218:221], v142 offset:3072
	ds_read_b128 v[222:225], v142 offset:4096
	ds_read_b128 v[226:229], v142 offset:5120
	ds_read_b128 v[230:233], v142 offset:6144
	ds_read_b128 v[234:237], v142 offset:7168
	global_load_lds_dwordx4 v[164:165], off
	v_lshl_add_u64 v[164:165], s[66:67], 0, v[138:139]
	s_add_i32 m0, s11, 0xe000
	s_nop 0
	global_load_lds_dwordx4 v[164:165], off
	s_waitcnt vmcnt(8)
	s_waitcnt lgkmcnt(0)
	s_setprio 1
	s_waitcnt lgkmcnt(0)
	v_mfma_f32_16x16x32_bf16 v[126:129], v[144:147], v[206:209], v[126:129]
	v_mfma_f32_16x16x32_bf16 v[122:125], v[152:155], v[206:209], v[122:125]
	v_mfma_f32_16x16x32_bf16 v[118:121], v[144:147], v[214:217], v[118:121]
	v_mfma_f32_16x16x32_bf16 v[114:117], v[152:155], v[214:217], v[114:117]
	s_barrier
	v_mfma_f32_16x16x32_bf16 v[102:105], v[144:147], v[222:225], v[102:105]
	v_mfma_f32_16x16x32_bf16 v[98:101], v[152:155], v[222:225], v[98:101]
	v_mfma_f32_16x16x32_bf16 v[86:89], v[144:147], v[230:233], v[86:89]
	v_mfma_f32_16x16x32_bf16 v[82:85], v[152:155], v[230:233], v[82:85]
	v_mfma_f32_16x16x32_bf16 v[126:129], v[148:151], v[210:213], v[126:129]
	v_mfma_f32_16x16x32_bf16 v[122:125], v[156:159], v[210:213], v[122:125]
	v_mfma_f32_16x16x32_bf16 v[118:121], v[148:151], v[218:221], v[118:121]
	v_mfma_f32_16x16x32_bf16 v[114:117], v[156:159], v[218:221], v[114:117]
	v_mfma_f32_16x16x32_bf16 v[102:105], v[148:151], v[226:229], v[102:105]
	v_mfma_f32_16x16x32_bf16 v[98:101], v[156:159], v[226:229], v[98:101]
	v_mfma_f32_16x16x32_bf16 v[86:89], v[148:151], v[234:237], v[86:89]
	v_mfma_f32_16x16x32_bf16 v[82:85], v[156:159], v[234:237], v[82:85]
	v_mfma_f32_16x16x32_bf16 v[110:113], v[160:163], v[206:209], v[110:113]
	v_mfma_f32_16x16x32_bf16 v[106:109], v[182:185], v[206:209], v[106:109]
	v_mfma_f32_16x16x32_bf16 v[94:97], v[160:163], v[214:217], v[94:97]
	v_mfma_f32_16x16x32_bf16 v[90:93], v[182:185], v[214:217], v[90:93]
	v_mfma_f32_16x16x32_bf16 v[78:81], v[160:163], v[222:225], v[78:81]
	v_mfma_f32_16x16x32_bf16 v[74:77], v[182:185], v[222:225], v[74:77]
	v_mfma_f32_16x16x32_bf16 v[70:73], v[160:163], v[230:233], v[70:73]
	v_mfma_f32_16x16x32_bf16 v[66:69], v[182:185], v[230:233], v[66:69]
	v_mfma_f32_16x16x32_bf16 v[110:113], v[178:181], v[210:213], v[110:113]
	v_mfma_f32_16x16x32_bf16 v[106:109], v[186:189], v[210:213], v[106:109]
	v_mfma_f32_16x16x32_bf16 v[94:97], v[178:181], v[218:221], v[94:97]
	v_mfma_f32_16x16x32_bf16 v[90:93], v[186:189], v[218:221], v[90:93]
	v_mfma_f32_16x16x32_bf16 v[78:81], v[178:181], v[226:229], v[78:81]
	v_mfma_f32_16x16x32_bf16 v[74:77], v[186:189], v[226:229], v[74:77]
	v_mfma_f32_16x16x32_bf16 v[70:73], v[178:181], v[234:237], v[70:73]
	v_mfma_f32_16x16x32_bf16 v[66:69], v[186:189], v[234:237], v[66:69]
	s_barrier
	s_setprio 0
	s_add_i32 s46, s62, s72
	v_lshl_add_u64 v[164:165], s[60:61], 0, v[166:167]
	s_mov_b32 m0, s46
	ds_read_b128 v[206:209], v142 offset:16384
	ds_read_b128 v[210:213], v142 offset:17408
	ds_read_b128 v[214:217], v142 offset:18432
	ds_read_b128 v[218:221], v142 offset:19456
	ds_read_b128 v[222:225], v142 offset:20480
	ds_read_b128 v[226:229], v142 offset:21504
	ds_read_b128 v[230:233], v142 offset:22528
	ds_read_b128 v[234:237], v142 offset:23552
	global_load_lds_dwordx4 v[164:165], off
	s_add_i32 m0, s46, 0x2000
	s_add_u32 s46, s60, 0x20000
	v_lshl_add_u64 v[242:243], s[60:61], 0, v[130:131]
	s_addc_u32 s47, s61, 0
	s_add_i32 s62, s63, s72
	global_load_lds_dwordx4 v[242:243], off
	v_lshl_add_u64 v[244:245], s[46:47], 0, v[166:167]
	s_mov_b32 m0, s62
	v_lshl_add_u64 v[246:247], s[68:69], 0, v[132:133]
	global_load_lds_dwordx4 v[244:245], off
	v_lshl_add_u64 v[244:245], s[46:47], 0, v[130:131]
	s_add_i32 m0, s62, 0x2000
	s_nop 0
	global_load_lds_dwordx4 v[244:245], off
	v_lshl_add_u64 v[244:245], s[68:69], 0, v[134:135]
	s_mov_b32 m0, s11
	s_nop 0
	global_load_lds_dwordx4 v[244:245], off
	s_mov_b32 m0, s74
	s_nop 0
	global_load_lds_dwordx4 v[246:247], off
	s_waitcnt vmcnt(8)
	s_waitcnt lgkmcnt(0)
	s_setprio 1
	s_waitcnt lgkmcnt(0)
	v_mfma_f32_16x16x32_bf16 v[62:65], v[144:147], v[206:209], v[62:65]
	v_mfma_f32_16x16x32_bf16 v[58:61], v[152:155], v[206:209], v[58:61]
	s_barrier
	v_mfma_f32_16x16x32_bf16 v[54:57], v[144:147], v[214:217], v[54:57]
	v_mfma_f32_16x16x32_bf16 v[50:53], v[152:155], v[214:217], v[50:53]
	v_mfma_f32_16x16x32_bf16 v[38:41], v[144:147], v[222:225], v[38:41]
	v_mfma_f32_16x16x32_bf16 v[34:37], v[152:155], v[222:225], v[34:37]
	v_mfma_f32_16x16x32_bf16 v[22:25], v[144:147], v[230:233], v[22:25]
	v_mfma_f32_16x16x32_bf16 v[18:21], v[152:155], v[230:233], v[18:21]
	v_mfma_f32_16x16x32_bf16 v[62:65], v[148:151], v[210:213], v[62:65]
	v_mfma_f32_16x16x32_bf16 v[58:61], v[156:159], v[210:213], v[58:61]
	v_mfma_f32_16x16x32_bf16 v[54:57], v[148:151], v[218:221], v[54:57]
	v_mfma_f32_16x16x32_bf16 v[50:53], v[156:159], v[218:221], v[50:53]
	v_mfma_f32_16x16x32_bf16 v[38:41], v[148:151], v[226:229], v[38:41]
	v_mfma_f32_16x16x32_bf16 v[34:37], v[156:159], v[226:229], v[34:37]
	v_mfma_f32_16x16x32_bf16 v[22:25], v[148:151], v[234:237], v[22:25]
	v_mfma_f32_16x16x32_bf16 v[18:21], v[156:159], v[234:237], v[18:21]
	v_mfma_f32_16x16x32_bf16 v[46:49], v[160:163], v[206:209], v[46:49]
	v_mfma_f32_16x16x32_bf16 v[42:45], v[182:185], v[206:209], v[42:45]
	v_mfma_f32_16x16x32_bf16 v[30:33], v[160:163], v[214:217], v[30:33]
	v_mfma_f32_16x16x32_bf16 v[26:29], v[182:185], v[214:217], v[26:29]
	v_mfma_f32_16x16x32_bf16 v[14:17], v[160:163], v[222:225], v[14:17]
	v_mfma_f32_16x16x32_bf16 v[10:13], v[182:185], v[222:225], v[10:13]
	v_mfma_f32_16x16x32_bf16 v[6:9], v[160:163], v[230:233], v[6:9]
	v_mfma_f32_16x16x32_bf16 v[2:5], v[182:185], v[230:233], v[2:5]
	v_mfma_f32_16x16x32_bf16 v[46:49], v[178:181], v[210:213], v[46:49]
	v_mfma_f32_16x16x32_bf16 v[42:45], v[186:189], v[210:213], v[42:45]
	v_mfma_f32_16x16x32_bf16 v[30:33], v[178:181], v[218:221], v[30:33]
	v_mfma_f32_16x16x32_bf16 v[26:29], v[186:189], v[218:221], v[26:29]
	v_mfma_f32_16x16x32_bf16 v[14:17], v[178:181], v[226:229], v[14:17]
	v_mfma_f32_16x16x32_bf16 v[10:13], v[186:189], v[226:229], v[10:13]
	v_mfma_f32_16x16x32_bf16 v[6:9], v[178:181], v[234:237], v[6:9]
	v_mfma_f32_16x16x32_bf16 v[2:5], v[186:189], v[234:237], v[2:5]
	s_barrier
	s_setprio 0
	s_add_i32 s62, 0, 0x18000
	v_add_u32_e32 v143, s62, v140
	s_add_i32 s63, 0, 0x1c000
	ds_read_b128 v[144:147], v143
	ds_read_b128 v[148:151], v143 offset:1024
	ds_read_b128 v[152:155], v143 offset:2048
	ds_read_b128 v[156:159], v143 offset:3072
	v_add_u32_e32 v143, s63, v140
	ds_read_b128 v[160:163], v143
	ds_read_b128 v[178:181], v143 offset:1024
	ds_read_b128 v[182:185], v143 offset:2048
	ds_read_b128 v[186:189], v143 offset:3072
	s_add_u32 s46, s68, 0x20000
	s_addc_u32 s47, s69, 0
	s_mov_b32 m0, s75
	v_lshl_add_u64 v[248:249], s[46:47], 0, v[134:135]
	ds_read_b128 v[206:209], v142 offset:32768
	ds_read_b128 v[210:213], v142 offset:33792
	ds_read_b128 v[214:217], v142 offset:34816
	ds_read_b128 v[218:221], v142 offset:35840
	ds_read_b128 v[222:225], v142 offset:36864
	ds_read_b128 v[226:229], v142 offset:37888
	ds_read_b128 v[230:233], v142 offset:38912
	ds_read_b128 v[234:237], v142 offset:39936
	global_load_lds_dwordx4 v[248:249], off
	v_lshl_add_u64 v[248:249], s[46:47], 0, v[132:133]
	s_mov_b32 m0, s76
	s_nop 0
	global_load_lds_dwordx4 v[248:249], off
	s_waitcnt vmcnt(8)
	s_waitcnt lgkmcnt(0)
	s_setprio 1
	s_waitcnt lgkmcnt(0)
	v_mfma_f32_16x16x32_bf16 v[126:129], v[144:147], v[206:209], v[126:129]
	v_mfma_f32_16x16x32_bf16 v[122:125], v[152:155], v[206:209], v[122:125]
	v_mfma_f32_16x16x32_bf16 v[118:121], v[144:147], v[214:217], v[118:121]
	v_mfma_f32_16x16x32_bf16 v[114:117], v[152:155], v[214:217], v[114:117]
	s_barrier
	v_mfma_f32_16x16x32_bf16 v[102:105], v[144:147], v[222:225], v[102:105]
	v_mfma_f32_16x16x32_bf16 v[98:101], v[152:155], v[222:225], v[98:101]
	v_mfma_f32_16x16x32_bf16 v[86:89], v[144:147], v[230:233], v[86:89]
	v_mfma_f32_16x16x32_bf16 v[82:85], v[152:155], v[230:233], v[82:85]
	v_mfma_f32_16x16x32_bf16 v[126:129], v[148:151], v[210:213], v[126:129]
	v_mfma_f32_16x16x32_bf16 v[122:125], v[156:159], v[210:213], v[122:125]
	v_mfma_f32_16x16x32_bf16 v[118:121], v[148:151], v[218:221], v[118:121]
	v_mfma_f32_16x16x32_bf16 v[114:117], v[156:159], v[218:221], v[114:117]
	v_mfma_f32_16x16x32_bf16 v[102:105], v[148:151], v[226:229], v[102:105]
	v_mfma_f32_16x16x32_bf16 v[98:101], v[156:159], v[226:229], v[98:101]
	v_mfma_f32_16x16x32_bf16 v[86:89], v[148:151], v[234:237], v[86:89]
	v_mfma_f32_16x16x32_bf16 v[82:85], v[156:159], v[234:237], v[82:85]
	v_mfma_f32_16x16x32_bf16 v[110:113], v[160:163], v[206:209], v[110:113]
	v_mfma_f32_16x16x32_bf16 v[106:109], v[182:185], v[206:209], v[106:109]
	v_mfma_f32_16x16x32_bf16 v[94:97], v[160:163], v[214:217], v[94:97]
	v_mfma_f32_16x16x32_bf16 v[90:93], v[182:185], v[214:217], v[90:93]
	v_mfma_f32_16x16x32_bf16 v[78:81], v[160:163], v[222:225], v[78:81]
	v_mfma_f32_16x16x32_bf16 v[74:77], v[182:185], v[222:225], v[74:77]
	v_mfma_f32_16x16x32_bf16 v[70:73], v[160:163], v[230:233], v[70:73]
	v_mfma_f32_16x16x32_bf16 v[66:69], v[182:185], v[230:233], v[66:69]
	v_mfma_f32_16x16x32_bf16 v[110:113], v[178:181], v[210:213], v[110:113]
	v_mfma_f32_16x16x32_bf16 v[106:109], v[186:189], v[210:213], v[106:109]
	v_mfma_f32_16x16x32_bf16 v[94:97], v[178:181], v[218:221], v[94:97]
	v_mfma_f32_16x16x32_bf16 v[90:93], v[186:189], v[218:221], v[90:93]
	v_mfma_f32_16x16x32_bf16 v[78:81], v[178:181], v[226:229], v[78:81]
	v_mfma_f32_16x16x32_bf16 v[74:77], v[186:189], v[226:229], v[74:77]
	v_mfma_f32_16x16x32_bf16 v[70:73], v[178:181], v[234:237], v[70:73]
	v_mfma_f32_16x16x32_bf16 v[66:69], v[186:189], v[234:237], v[66:69]
	s_barrier
	s_setprio 0
	s_add_i32 s46, s62, s72
	v_lshl_add_u64 v[164:165], v[164:165], 0, s[42:43]
	s_mov_b32 m0, s46
	ds_read_b128 v[206:209], v142 offset:49152
	ds_read_b128 v[210:213], v142 offset:50176
	ds_read_b128 v[214:217], v142 offset:51200
	ds_read_b128 v[218:221], v142 offset:52224
	ds_read_b128 v[222:225], v142 offset:53248
	ds_read_b128 v[226:229], v142 offset:54272
	ds_read_b128 v[230:233], v142 offset:55296
	ds_read_b128 v[234:237], v142 offset:56320
	global_load_lds_dwordx4 v[164:165], off
	s_add_i32 m0, s46, 0x2000
	s_add_u32 s46, s60, 0x20080
	v_lshl_add_u64 v[164:165], v[242:243], 0, s[42:43]
	s_addc_u32 s47, s61, 0
	s_add_i32 s60, s63, s72
	global_load_lds_dwordx4 v[164:165], off
	v_lshl_add_u64 v[164:165], s[46:47], 0, v[166:167]
	s_mov_b32 m0, s60
	s_nop 0
	global_load_lds_dwordx4 v[164:165], off
	v_lshl_add_u64 v[164:165], s[46:47], 0, v[130:131]
	s_add_i32 m0, s60, 0x2000
	s_nop 0
	global_load_lds_dwordx4 v[164:165], off
	v_lshl_add_u64 v[164:165], v[244:245], 0, s[42:43]
	s_mov_b32 m0, s77
	s_nop 0
	global_load_lds_dwordx4 v[164:165], off
	v_lshl_add_u64 v[164:165], v[246:247], 0, s[42:43]
	s_mov_b32 m0, s78
	s_nop 0
	global_load_lds_dwordx4 v[164:165], off
	s_waitcnt vmcnt(8)
	s_waitcnt lgkmcnt(0)
	s_setprio 1
	s_waitcnt lgkmcnt(0)
	v_mfma_f32_16x16x32_bf16 v[62:65], v[144:147], v[206:209], v[62:65]
	v_mfma_f32_16x16x32_bf16 v[58:61], v[152:155], v[206:209], v[58:61]
	s_barrier
	v_mfma_f32_16x16x32_bf16 v[54:57], v[144:147], v[214:217], v[54:57]
	v_mfma_f32_16x16x32_bf16 v[50:53], v[152:155], v[214:217], v[50:53]
	v_mfma_f32_16x16x32_bf16 v[38:41], v[144:147], v[222:225], v[38:41]
	v_mfma_f32_16x16x32_bf16 v[34:37], v[152:155], v[222:225], v[34:37]
	v_mfma_f32_16x16x32_bf16 v[22:25], v[144:147], v[230:233], v[22:25]
	v_mfma_f32_16x16x32_bf16 v[18:21], v[152:155], v[230:233], v[18:21]
	v_mfma_f32_16x16x32_bf16 v[62:65], v[148:151], v[210:213], v[62:65]
	v_mfma_f32_16x16x32_bf16 v[58:61], v[156:159], v[210:213], v[58:61]
	v_mfma_f32_16x16x32_bf16 v[54:57], v[148:151], v[218:221], v[54:57]
	v_mfma_f32_16x16x32_bf16 v[50:53], v[156:159], v[218:221], v[50:53]
	v_mfma_f32_16x16x32_bf16 v[38:41], v[148:151], v[226:229], v[38:41]
	v_mfma_f32_16x16x32_bf16 v[34:37], v[156:159], v[226:229], v[34:37]
	v_mfma_f32_16x16x32_bf16 v[22:25], v[148:151], v[234:237], v[22:25]
	v_mfma_f32_16x16x32_bf16 v[18:21], v[156:159], v[234:237], v[18:21]
	v_mfma_f32_16x16x32_bf16 v[46:49], v[160:163], v[206:209], v[46:49]
	v_mfma_f32_16x16x32_bf16 v[42:45], v[182:185], v[206:209], v[42:45]
	v_mfma_f32_16x16x32_bf16 v[30:33], v[160:163], v[214:217], v[30:33]
	v_mfma_f32_16x16x32_bf16 v[26:29], v[182:185], v[214:217], v[26:29]
	v_mfma_f32_16x16x32_bf16 v[14:17], v[160:163], v[222:225], v[14:17]
	v_mfma_f32_16x16x32_bf16 v[10:13], v[182:185], v[222:225], v[10:13]
	v_mfma_f32_16x16x32_bf16 v[6:9], v[160:163], v[230:233], v[6:9]
	v_mfma_f32_16x16x32_bf16 v[2:5], v[182:185], v[230:233], v[2:5]
	v_mfma_f32_16x16x32_bf16 v[46:49], v[178:181], v[210:213], v[46:49]
	v_mfma_f32_16x16x32_bf16 v[42:45], v[186:189], v[210:213], v[42:45]
	v_mfma_f32_16x16x32_bf16 v[30:33], v[178:181], v[218:221], v[30:33]
	v_mfma_f32_16x16x32_bf16 v[26:29], v[186:189], v[218:221], v[26:29]
	v_mfma_f32_16x16x32_bf16 v[14:17], v[178:181], v[226:229], v[14:17]
	v_mfma_f32_16x16x32_bf16 v[10:13], v[186:189], v[226:229], v[10:13]
	v_mfma_f32_16x16x32_bf16 v[6:9], v[178:181], v[234:237], v[6:9]
	v_mfma_f32_16x16x32_bf16 v[2:5], v[186:189], v[234:237], v[2:5]
	s_barrier
	s_setprio 0
	s_add_i32 s84, s84, 2
	s_add_u32 s66, s66, 0x100
	s_addc_u32 s67, s67, 0
	s_add_u32 s82, s82, 0x100
	s_addc_u32 s83, s83, 0
	s_cmp_gt_u32 s84, 5
	s_cbranch_scc0 .LBB0_426
	s_and_b64 vcc, exec, s[12:13]
	s_cbranch_vccz .LBB0_429
	s_barrier

.LBB0_442:
	s_add_u32 s62, s18, s72
	s_addc_u32 s63, s19, 0
	s_add_u32 s73, s62, 0x100
	s_addc_u32 s74, s63, 0
	s_and_b64 s[46:47], s[60:61], exec
	s_cselect_b32 s75, s23, s74
	s_cselect_b32 s74, s92, s73
	s_add_u32 s46, s16, s72
	s_addc_u32 s47, s17, 0
	s_add_u32 s72, s46, 0x100
	s_addc_u32 s73, s47, 0
	s_add_i32 s48, 0, 0x10000
	s_and_b64 s[46:47], s[60:61], exec
	s_cselect_b32 s77, s21, s73
	s_cselect_b32 s76, s93, s72
	s_add_i32 s46, 0, 0x14000
	s_add_u32 s80, s62, 0x10080
	s_addc_u32 s81, s63, 0
	s_add_i32 s63, s48, s84
	s_add_i32 m0, s13, 0xc000
	s_add_i32 s49, s13, 0xe000
	s_add_i32 vcc_lo, s63, 0x2000
	v_add_u32_e32 v139, s48, v136
	s_add_u32 s78, s76, 0x10000
	ds_read_b128 v[140:143], v139
	ds_read_b128 v[144:147], v139 offset:1024
	ds_read_b128 v[148:151], v139 offset:2048
	ds_read_b128 v[152:155], v139 offset:3072
	v_add_u32_e32 v139, s46, v136
	s_addc_u32 s79, s77, 0
	s_add_i32 vcc_hi, s46, s84
	ds_read_b128 v[156:159], v139
	ds_read_b128 v[160:163], v139 offset:1024
	ds_read_b128 v[178:181], v139 offset:2048
	ds_read_b128 v[182:185], v139 offset:3072
	s_add_i32 s62, vcc_hi, 0x2000
	s_add_i32 s97, 0, 0x18000
	s_add_i32 s96, 0, 0x1c000
	s_add_u32 s72, s74, 0x10000
	s_addc_u32 s73, s75, 0
	s_add_i32 s95, s97, s84
	s_add_i32 s94, s95, 0x2000
	s_add_u32 s60, s76, 0x10080
	s_addc_u32 s61, s77, 0
	s_add_i32 s47, s96, s84
	s_add_i32 s46, s47, 0x2000
	v_lshl_add_u64 v[164:165], s[80:81], 0, v[134:135]
	ds_read_b128 v[186:189], v138
	ds_read_b128 v[206:209], v138 offset:1024
	ds_read_b128 v[210:213], v138 offset:2048
	ds_read_b128 v[214:217], v138 offset:3072
	ds_read_b128 v[218:221], v138 offset:4096
	ds_read_b128 v[222:225], v138 offset:5120
	ds_read_b128 v[226:229], v138 offset:6144
	ds_read_b128 v[230:233], v138 offset:7168
	global_load_lds_dwordx4 v[164:165], off
	v_lshl_add_u64 v[164:165], s[80:81], 0, v[132:133]
	s_mov_b32 m0, s49
	s_nop 0
	global_load_lds_dwordx4 v[164:165], off
	s_waitcnt vmcnt(8)
	s_waitcnt lgkmcnt(0)
	s_setprio 1
	s_waitcnt lgkmcnt(0)
	v_mfma_f32_16x16x32_bf16 v[126:129], v[140:143], v[186:189], v[126:129]
	v_mfma_f32_16x16x32_bf16 v[122:125], v[148:151], v[186:189], v[122:125]
	v_mfma_f32_16x16x32_bf16 v[118:121], v[140:143], v[210:213], v[118:121]
	v_mfma_f32_16x16x32_bf16 v[114:117], v[148:151], v[210:213], v[114:117]
	s_barrier
	v_mfma_f32_16x16x32_bf16 v[102:105], v[140:143], v[218:221], v[102:105]
	v_mfma_f32_16x16x32_bf16 v[98:101], v[148:151], v[218:221], v[98:101]
	v_mfma_f32_16x16x32_bf16 v[86:89], v[140:143], v[226:229], v[86:89]
	v_mfma_f32_16x16x32_bf16 v[82:85], v[148:151], v[226:229], v[82:85]
	v_mfma_f32_16x16x32_bf16 v[126:129], v[144:147], v[206:209], v[126:129]
	v_mfma_f32_16x16x32_bf16 v[122:125], v[152:155], v[206:209], v[122:125]
	v_mfma_f32_16x16x32_bf16 v[118:121], v[144:147], v[214:217], v[118:121]
	v_mfma_f32_16x16x32_bf16 v[114:117], v[152:155], v[214:217], v[114:117]
	v_mfma_f32_16x16x32_bf16 v[102:105], v[144:147], v[222:225], v[102:105]
	v_mfma_f32_16x16x32_bf16 v[98:101], v[152:155], v[222:225], v[98:101]
	v_mfma_f32_16x16x32_bf16 v[86:89], v[144:147], v[230:233], v[86:89]
	v_mfma_f32_16x16x32_bf16 v[82:85], v[152:155], v[230:233], v[82:85]
	v_mfma_f32_16x16x32_bf16 v[110:113], v[156:159], v[186:189], v[110:113]
	v_mfma_f32_16x16x32_bf16 v[106:109], v[178:181], v[186:189], v[106:109]
	v_mfma_f32_16x16x32_bf16 v[94:97], v[156:159], v[210:213], v[94:97]
	v_mfma_f32_16x16x32_bf16 v[90:93], v[178:181], v[210:213], v[90:93]
	v_mfma_f32_16x16x32_bf16 v[78:81], v[156:159], v[218:221], v[78:81]
	v_mfma_f32_16x16x32_bf16 v[74:77], v[178:181], v[218:221], v[74:77]
	v_mfma_f32_16x16x32_bf16 v[70:73], v[156:159], v[226:229], v[70:73]
	v_mfma_f32_16x16x32_bf16 v[66:69], v[178:181], v[226:229], v[66:69]
	v_mfma_f32_16x16x32_bf16 v[110:113], v[160:163], v[206:209], v[110:113]
	v_mfma_f32_16x16x32_bf16 v[106:109], v[182:185], v[206:209], v[106:109]
	v_mfma_f32_16x16x32_bf16 v[94:97], v[160:163], v[214:217], v[94:97]
	v_mfma_f32_16x16x32_bf16 v[90:93], v[182:185], v[214:217], v[90:93]
	v_mfma_f32_16x16x32_bf16 v[78:81], v[160:163], v[222:225], v[78:81]
	v_mfma_f32_16x16x32_bf16 v[74:77], v[182:185], v[222:225], v[74:77]
	v_mfma_f32_16x16x32_bf16 v[70:73], v[160:163], v[230:233], v[70:73]
	v_mfma_f32_16x16x32_bf16 v[66:69], v[182:185], v[230:233], v[66:69]
	s_barrier
	s_setprio 0
	s_mov_b32 m0, s63
	v_lshl_add_u64 v[164:165], s[76:77], 0, v[166:167]
	ds_read_b128 v[186:189], v138 offset:16384
	ds_read_b128 v[206:209], v138 offset:17408
	ds_read_b128 v[210:213], v138 offset:18432
	ds_read_b128 v[214:217], v138 offset:19456
	ds_read_b128 v[218:221], v138 offset:20480
	ds_read_b128 v[222:225], v138 offset:21504
	ds_read_b128 v[226:229], v138 offset:22528
	ds_read_b128 v[230:233], v138 offset:23552
	global_load_lds_dwordx4 v[164:165], off
	v_lshl_add_u64 v[234:235], s[76:77], 0, v[130:131]
	s_mov_b32 m0, vcc_lo
	v_lshl_add_u64 v[236:237], s[78:79], 0, v[166:167]
	global_load_lds_dwordx4 v[234:235], off
	s_mov_b32 m0, vcc_hi
	v_lshl_add_u64 v[242:243], s[74:75], 0, v[132:133]
	global_load_lds_dwordx4 v[236:237], off
	v_lshl_add_u64 v[236:237], s[78:79], 0, v[130:131]
	s_mov_b32 m0, s62
	s_nop 0
	global_load_lds_dwordx4 v[236:237], off
	v_lshl_add_u64 v[236:237], s[74:75], 0, v[134:135]
	s_mov_b32 m0, s13
	s_nop 0
	global_load_lds_dwordx4 v[236:237], off
	s_mov_b32 m0, s86
	s_nop 0
	global_load_lds_dwordx4 v[242:243], off
	s_waitcnt vmcnt(8)
	s_waitcnt lgkmcnt(0)
	s_setprio 1
	s_waitcnt lgkmcnt(0)
	v_mfma_f32_16x16x32_bf16 v[62:65], v[140:143], v[186:189], v[62:65]
	v_mfma_f32_16x16x32_bf16 v[58:61], v[148:151], v[186:189], v[58:61]
	s_barrier
	v_mfma_f32_16x16x32_bf16 v[54:57], v[140:143], v[210:213], v[54:57]
	v_mfma_f32_16x16x32_bf16 v[50:53], v[148:151], v[210:213], v[50:53]
	v_mfma_f32_16x16x32_bf16 v[38:41], v[140:143], v[218:221], v[38:41]
	v_mfma_f32_16x16x32_bf16 v[34:37], v[148:151], v[218:221], v[34:37]
	v_mfma_f32_16x16x32_bf16 v[22:25], v[140:143], v[226:229], v[22:25]
	v_mfma_f32_16x16x32_bf16 v[18:21], v[148:151], v[226:229], v[18:21]
	v_mfma_f32_16x16x32_bf16 v[62:65], v[144:147], v[206:209], v[62:65]
	v_mfma_f32_16x16x32_bf16 v[58:61], v[152:155], v[206:209], v[58:61]
	v_mfma_f32_16x16x32_bf16 v[54:57], v[144:147], v[214:217], v[54:57]
	v_mfma_f32_16x16x32_bf16 v[50:53], v[152:155], v[214:217], v[50:53]
	v_mfma_f32_16x16x32_bf16 v[38:41], v[144:147], v[222:225], v[38:41]
	v_mfma_f32_16x16x32_bf16 v[34:37], v[152:155], v[222:225], v[34:37]
	v_mfma_f32_16x16x32_bf16 v[22:25], v[144:147], v[230:233], v[22:25]
	v_mfma_f32_16x16x32_bf16 v[18:21], v[152:155], v[230:233], v[18:21]
	v_mfma_f32_16x16x32_bf16 v[46:49], v[156:159], v[186:189], v[46:49]
	v_mfma_f32_16x16x32_bf16 v[42:45], v[178:181], v[186:189], v[42:45]
	v_mfma_f32_16x16x32_bf16 v[30:33], v[156:159], v[210:213], v[30:33]
	v_mfma_f32_16x16x32_bf16 v[26:29], v[178:181], v[210:213], v[26:29]
	v_mfma_f32_16x16x32_bf16 v[14:17], v[156:159], v[218:221], v[14:17]
	v_mfma_f32_16x16x32_bf16 v[10:13], v[178:181], v[218:221], v[10:13]
	v_mfma_f32_16x16x32_bf16 v[6:9], v[156:159], v[226:229], v[6:9]
	v_mfma_f32_16x16x32_bf16 v[2:5], v[178:181], v[226:229], v[2:5]
	v_mfma_f32_16x16x32_bf16 v[46:49], v[160:163], v[206:209], v[46:49]
	v_mfma_f32_16x16x32_bf16 v[42:45], v[182:185], v[206:209], v[42:45]
	v_mfma_f32_16x16x32_bf16 v[30:33], v[160:163], v[214:217], v[30:33]
	v_mfma_f32_16x16x32_bf16 v[26:29], v[182:185], v[214:217], v[26:29]
	v_mfma_f32_16x16x32_bf16 v[14:17], v[160:163], v[222:225], v[14:17]
	v_mfma_f32_16x16x32_bf16 v[10:13], v[182:185], v[222:225], v[10:13]
	v_mfma_f32_16x16x32_bf16 v[6:9], v[160:163], v[230:233], v[6:9]
	v_mfma_f32_16x16x32_bf16 v[2:5], v[182:185], v[230:233], v[2:5]
	s_barrier
	s_setprio 0
	v_add_u32_e32 v139, s97, v136
	ds_read_b128 v[140:143], v139
	ds_read_b128 v[144:147], v139 offset:1024
	ds_read_b128 v[148:151], v139 offset:2048
	ds_read_b128 v[152:155], v139 offset:3072
	v_add_u32_e32 v139, s96, v136
	ds_read_b128 v[156:159], v139
	ds_read_b128 v[160:163], v139 offset:1024
	ds_read_b128 v[178:181], v139 offset:2048
	ds_read_b128 v[182:185], v139 offset:3072
	s_mov_b32 m0, s87
	v_lshl_add_u64 v[244:245], s[72:73], 0, v[134:135]
	ds_read_b128 v[186:189], v138 offset:32768
	ds_read_b128 v[206:209], v138 offset:33792
	ds_read_b128 v[210:213], v138 offset:34816
	ds_read_b128 v[214:217], v138 offset:35840
	ds_read_b128 v[218:221], v138 offset:36864
	ds_read_b128 v[222:225], v138 offset:37888
	ds_read_b128 v[226:229], v138 offset:38912
	ds_read_b128 v[230:233], v138 offset:39936
	global_load_lds_dwordx4 v[244:245], off
	v_lshl_add_u64 v[244:245], s[72:73], 0, v[132:133]
	s_mov_b32 m0, s88
	s_nop 0
	global_load_lds_dwordx4 v[244:245], off
	s_waitcnt vmcnt(8)
	s_waitcnt lgkmcnt(0)
	s_setprio 1
	s_waitcnt lgkmcnt(0)
	v_mfma_f32_16x16x32_bf16 v[126:129], v[140:143], v[186:189], v[126:129]
	v_mfma_f32_16x16x32_bf16 v[122:125], v[148:151], v[186:189], v[122:125]
	v_mfma_f32_16x16x32_bf16 v[118:121], v[140:143], v[210:213], v[118:121]
	v_mfma_f32_16x16x32_bf16 v[114:117], v[148:151], v[210:213], v[114:117]
	s_barrier
	v_mfma_f32_16x16x32_bf16 v[102:105], v[140:143], v[218:221], v[102:105]
	v_mfma_f32_16x16x32_bf16 v[98:101], v[148:151], v[218:221], v[98:101]
	v_mfma_f32_16x16x32_bf16 v[86:89], v[140:143], v[226:229], v[86:89]
	v_mfma_f32_16x16x32_bf16 v[82:85], v[148:151], v[226:229], v[82:85]
	v_mfma_f32_16x16x32_bf16 v[126:129], v[144:147], v[206:209], v[126:129]
	v_mfma_f32_16x16x32_bf16 v[122:125], v[152:155], v[206:209], v[122:125]
	v_mfma_f32_16x16x32_bf16 v[118:121], v[144:147], v[214:217], v[118:121]
	v_mfma_f32_16x16x32_bf16 v[114:117], v[152:155], v[214:217], v[114:117]
	v_mfma_f32_16x16x32_bf16 v[102:105], v[144:147], v[222:225], v[102:105]
	v_mfma_f32_16x16x32_bf16 v[98:101], v[152:155], v[222:225], v[98:101]
	v_mfma_f32_16x16x32_bf16 v[86:89], v[144:147], v[230:233], v[86:89]
	v_mfma_f32_16x16x32_bf16 v[82:85], v[152:155], v[230:233], v[82:85]
	v_mfma_f32_16x16x32_bf16 v[110:113], v[156:159], v[186:189], v[110:113]
	v_mfma_f32_16x16x32_bf16 v[106:109], v[178:181], v[186:189], v[106:109]
	v_mfma_f32_16x16x32_bf16 v[94:97], v[156:159], v[210:213], v[94:97]
	v_mfma_f32_16x16x32_bf16 v[90:93], v[178:181], v[210:213], v[90:93]
	v_mfma_f32_16x16x32_bf16 v[78:81], v[156:159], v[218:221], v[78:81]
	v_mfma_f32_16x16x32_bf16 v[74:77], v[178:181], v[218:221], v[74:77]
	v_mfma_f32_16x16x32_bf16 v[70:73], v[156:159], v[226:229], v[70:73]
	v_mfma_f32_16x16x32_bf16 v[66:69], v[178:181], v[226:229], v[66:69]
	v_mfma_f32_16x16x32_bf16 v[110:113], v[160:163], v[206:209], v[110:113]
	v_mfma_f32_16x16x32_bf16 v[106:109], v[182:185], v[206:209], v[106:109]
	v_mfma_f32_16x16x32_bf16 v[94:97], v[160:163], v[214:217], v[94:97]
	v_mfma_f32_16x16x32_bf16 v[90:93], v[182:185], v[214:217], v[90:93]
	v_mfma_f32_16x16x32_bf16 v[78:81], v[160:163], v[222:225], v[78:81]
	v_mfma_f32_16x16x32_bf16 v[74:77], v[182:185], v[222:225], v[74:77]
	v_mfma_f32_16x16x32_bf16 v[70:73], v[160:163], v[230:233], v[70:73]
	v_mfma_f32_16x16x32_bf16 v[66:69], v[182:185], v[230:233], v[66:69]
	s_barrier
	s_setprio 0
	s_mov_b32 m0, s95
	v_lshl_add_u64 v[164:165], v[164:165], 0, s[42:43]
	ds_read_b128 v[186:189], v138 offset:49152
	ds_read_b128 v[206:209], v138 offset:50176
	ds_read_b128 v[210:213], v138 offset:51200
	ds_read_b128 v[214:217], v138 offset:52224
	ds_read_b128 v[218:221], v138 offset:53248
	ds_read_b128 v[222:225], v138 offset:54272
	ds_read_b128 v[226:229], v138 offset:55296
	ds_read_b128 v[230:233], v138 offset:56320
	global_load_lds_dwordx4 v[164:165], off
	v_lshl_add_u64 v[164:165], v[234:235], 0, s[42:43]
	s_mov_b32 m0, s94
	s_nop 0
	global_load_lds_dwordx4 v[164:165], off
	v_lshl_add_u64 v[164:165], s[60:61], 0, v[166:167]
	s_mov_b32 m0, s47
	s_nop 0
	global_load_lds_dwordx4 v[164:165], off
	v_lshl_add_u64 v[164:165], s[60:61], 0, v[130:131]
	s_mov_b32 m0, s46
	s_nop 0
	global_load_lds_dwordx4 v[164:165], off
	v_lshl_add_u64 v[164:165], v[236:237], 0, s[42:43]
	s_mov_b32 m0, s89
	s_nop 0
	global_load_lds_dwordx4 v[164:165], off
	v_lshl_add_u64 v[164:165], v[242:243], 0, s[42:43]
	s_mov_b32 m0, s90
	s_nop 0
	global_load_lds_dwordx4 v[164:165], off
	s_waitcnt vmcnt(8)
	s_waitcnt lgkmcnt(0)
	s_setprio 1
	s_waitcnt lgkmcnt(0)
	v_mfma_f32_16x16x32_bf16 v[62:65], v[140:143], v[186:189], v[62:65]
	v_mfma_f32_16x16x32_bf16 v[58:61], v[148:151], v[186:189], v[58:61]
	s_barrier
	v_mfma_f32_16x16x32_bf16 v[54:57], v[140:143], v[210:213], v[54:57]
	v_mfma_f32_16x16x32_bf16 v[50:53], v[148:151], v[210:213], v[50:53]
	v_mfma_f32_16x16x32_bf16 v[38:41], v[140:143], v[218:221], v[38:41]
	v_mfma_f32_16x16x32_bf16 v[34:37], v[148:151], v[218:221], v[34:37]
	v_mfma_f32_16x16x32_bf16 v[22:25], v[140:143], v[226:229], v[22:25]
	v_mfma_f32_16x16x32_bf16 v[18:21], v[148:151], v[226:229], v[18:21]
	v_mfma_f32_16x16x32_bf16 v[62:65], v[144:147], v[206:209], v[62:65]
	v_mfma_f32_16x16x32_bf16 v[58:61], v[152:155], v[206:209], v[58:61]
	v_mfma_f32_16x16x32_bf16 v[54:57], v[144:147], v[214:217], v[54:57]
	v_mfma_f32_16x16x32_bf16 v[50:53], v[152:155], v[214:217], v[50:53]
	v_mfma_f32_16x16x32_bf16 v[38:41], v[144:147], v[222:225], v[38:41]
	v_mfma_f32_16x16x32_bf16 v[34:37], v[152:155], v[222:225], v[34:37]
	v_mfma_f32_16x16x32_bf16 v[22:25], v[144:147], v[230:233], v[22:25]
	v_mfma_f32_16x16x32_bf16 v[18:21], v[152:155], v[230:233], v[18:21]
	v_mfma_f32_16x16x32_bf16 v[46:49], v[156:159], v[186:189], v[46:49]
	v_mfma_f32_16x16x32_bf16 v[42:45], v[178:181], v[186:189], v[42:45]
	v_mfma_f32_16x16x32_bf16 v[30:33], v[156:159], v[210:213], v[30:33]
	v_mfma_f32_16x16x32_bf16 v[26:29], v[178:181], v[210:213], v[26:29]
	v_mfma_f32_16x16x32_bf16 v[14:17], v[156:159], v[218:221], v[14:17]
	v_mfma_f32_16x16x32_bf16 v[10:13], v[178:181], v[218:221], v[10:13]
	v_mfma_f32_16x16x32_bf16 v[6:9], v[156:159], v[226:229], v[6:9]
	v_mfma_f32_16x16x32_bf16 v[2:5], v[178:181], v[226:229], v[2:5]
	v_mfma_f32_16x16x32_bf16 v[46:49], v[160:163], v[206:209], v[46:49]
	v_mfma_f32_16x16x32_bf16 v[42:45], v[182:185], v[206:209], v[42:45]
	v_mfma_f32_16x16x32_bf16 v[30:33], v[160:163], v[214:217], v[30:33]
	v_mfma_f32_16x16x32_bf16 v[26:29], v[182:185], v[214:217], v[26:29]
	v_mfma_f32_16x16x32_bf16 v[14:17], v[160:163], v[222:225], v[14:17]
	v_mfma_f32_16x16x32_bf16 v[10:13], v[182:185], v[222:225], v[10:13]
	v_mfma_f32_16x16x32_bf16 v[6:9], v[160:163], v[230:233], v[6:9]
	v_mfma_f32_16x16x32_bf16 v[2:5], v[182:185], v[230:233], v[2:5]
	s_barrier
	s_setprio 0
	s_movk_i32 s72, 0x100
	s_andn2_b64 vcc, exec, s[70:71]
	s_mov_b64 s[60:61], -1
	s_mov_b64 s[70:71], 0
	s_cbranch_vccz .LBB0_442
	s_and_b64 vcc, exec, s[10:11]
	s_cbranch_vccz .LBB0_445
	s_barrier

.LBB0_795:
	s_add_u32 s46, s68, 0xfff80080
	s_addc_u32 s47, s69, -1
	s_add_i32 s48, 0, 0x10000
	s_cmp_eq_u32 s87, 28
	s_cselect_b32 s71, s19, s47
	s_cselect_b32 s70, s83, s46
	s_cselect_b32 s61, s17, s86
	s_cselect_b32 s60, s84, s85
	s_add_i32 s49, 0, 0x14000
	v_add_u32_e32 v156, s48, v1
	v_add_u32_e32 v164, s49, v1
	ds_read_b128 v[130:133], v156
	ds_read_b128 v[134:137], v156 offset:1024
	ds_read_b128 v[150:153], v156 offset:2048
	ds_read_b128 v[156:159], v156 offset:3072
	ds_read_b128 v[160:163], v164
	ds_read_b128 v[178:181], v164 offset:1024
	ds_read_b128 v[182:185], v164 offset:2048
	ds_read_b128 v[186:189], v164 offset:3072
	v_lshl_add_u64 v[164:165], s[68:69], 0, v[146:147]
	s_add_i32 m0, s67, 0xc000
	ds_read_b128 v[206:209], v155
	ds_read_b128 v[210:213], v155 offset:1024
	ds_read_b128 v[214:217], v155 offset:2048
	ds_read_b128 v[218:221], v155 offset:3072
	ds_read_b128 v[222:225], v155 offset:4096
	ds_read_b128 v[226:229], v155 offset:5120
	ds_read_b128 v[230:233], v155 offset:6144
	ds_read_b128 v[234:237], v155 offset:7168
	global_load_lds_dwordx4 v[164:165], off
	v_lshl_add_u64 v[164:165], s[68:69], 0, v[148:149]
	s_add_i32 m0, s67, 0xe000
	s_nop 0
	global_load_lds_dwordx4 v[164:165], off
	s_waitcnt vmcnt(8)
	s_waitcnt lgkmcnt(0)
	s_setprio 1
	s_waitcnt lgkmcnt(0)
	v_mfma_f32_16x16x32_bf16 v[126:129], v[130:133], v[206:209], v[126:129]
	v_mfma_f32_16x16x32_bf16 v[122:125], v[150:153], v[206:209], v[122:125]
	v_mfma_f32_16x16x32_bf16 v[118:121], v[130:133], v[214:217], v[118:121]
	v_mfma_f32_16x16x32_bf16 v[114:117], v[150:153], v[214:217], v[114:117]
	s_barrier
	v_mfma_f32_16x16x32_bf16 v[110:113], v[130:133], v[222:225], v[110:113]
	v_mfma_f32_16x16x32_bf16 v[106:109], v[150:153], v[222:225], v[106:109]
	v_mfma_f32_16x16x32_bf16 v[102:105], v[130:133], v[230:233], v[102:105]
	v_mfma_f32_16x16x32_bf16 v[98:101], v[150:153], v[230:233], v[98:101]
	v_mfma_f32_16x16x32_bf16 v[126:129], v[134:137], v[210:213], v[126:129]
	v_mfma_f32_16x16x32_bf16 v[122:125], v[156:159], v[210:213], v[122:125]
	v_mfma_f32_16x16x32_bf16 v[118:121], v[134:137], v[218:221], v[118:121]
	v_mfma_f32_16x16x32_bf16 v[114:117], v[156:159], v[218:221], v[114:117]
	v_mfma_f32_16x16x32_bf16 v[110:113], v[134:137], v[226:229], v[110:113]
	v_mfma_f32_16x16x32_bf16 v[106:109], v[156:159], v[226:229], v[106:109]
	v_mfma_f32_16x16x32_bf16 v[102:105], v[134:137], v[234:237], v[102:105]
	v_mfma_f32_16x16x32_bf16 v[98:101], v[156:159], v[234:237], v[98:101]
	v_mfma_f32_16x16x32_bf16 v[66:69], v[160:163], v[206:209], v[66:69]
	v_mfma_f32_16x16x32_bf16 v[58:61], v[182:185], v[206:209], v[58:61]
	v_mfma_f32_16x16x32_bf16 v[54:57], v[160:163], v[214:217], v[54:57]
	v_mfma_f32_16x16x32_bf16 v[50:53], v[182:185], v[214:217], v[50:53]
	v_mfma_f32_16x16x32_bf16 v[46:49], v[160:163], v[222:225], v[46:49]
	v_mfma_f32_16x16x32_bf16 v[42:45], v[182:185], v[222:225], v[42:45]
	v_mfma_f32_16x16x32_bf16 v[38:41], v[160:163], v[230:233], v[38:41]
	v_mfma_f32_16x16x32_bf16 v[34:37], v[182:185], v[230:233], v[34:37]
	v_mfma_f32_16x16x32_bf16 v[66:69], v[178:181], v[210:213], v[66:69]
	v_mfma_f32_16x16x32_bf16 v[58:61], v[186:189], v[210:213], v[58:61]
	v_mfma_f32_16x16x32_bf16 v[54:57], v[178:181], v[218:221], v[54:57]
	v_mfma_f32_16x16x32_bf16 v[50:53], v[186:189], v[218:221], v[50:53]
	v_mfma_f32_16x16x32_bf16 v[46:49], v[178:181], v[226:229], v[46:49]
	v_mfma_f32_16x16x32_bf16 v[42:45], v[186:189], v[226:229], v[42:45]
	v_mfma_f32_16x16x32_bf16 v[38:41], v[178:181], v[234:237], v[38:41]
	v_mfma_f32_16x16x32_bf16 v[34:37], v[186:189], v[234:237], v[34:37]
	s_barrier
	s_setprio 0
	s_add_i32 s46, s48, s77
	v_lshl_add_u64 v[164:165], s[60:61], 0, v[166:167]
	s_mov_b32 m0, s46
	ds_read_b128 v[206:209], v155 offset:16384
	ds_read_b128 v[210:213], v155 offset:17408
	ds_read_b128 v[214:217], v155 offset:18432
	ds_read_b128 v[218:221], v155 offset:19456
	ds_read_b128 v[222:225], v155 offset:20480
	ds_read_b128 v[226:229], v155 offset:21504
	ds_read_b128 v[230:233], v155 offset:22528
	ds_read_b128 v[234:237], v155 offset:23552
	global_load_lds_dwordx4 v[164:165], off
	s_add_i32 m0, s46, 0x2000
	s_add_u32 s46, s60, 0x80000
	v_lshl_add_u64 v[242:243], s[60:61], 0, v[142:143]
	s_addc_u32 s47, s61, 0
	s_add_i32 s48, s49, s77
	global_load_lds_dwordx4 v[242:243], off
	v_lshl_add_u64 v[244:245], s[46:47], 0, v[166:167]
	s_mov_b32 m0, s48
	v_lshl_add_u64 v[246:247], s[70:71], 0, v[140:141]
	global_load_lds_dwordx4 v[244:245], off
	v_lshl_add_u64 v[244:245], s[46:47], 0, v[142:143]
	s_add_i32 m0, s48, 0x2000
	s_nop 0
	global_load_lds_dwordx4 v[244:245], off
	v_lshl_add_u64 v[244:245], s[70:71], 0, v[138:139]
	s_mov_b32 m0, s67
	s_nop 0
	global_load_lds_dwordx4 v[244:245], off
	s_mov_b32 m0, s78
	s_nop 0
	global_load_lds_dwordx4 v[246:247], off
	s_waitcnt vmcnt(8)
	s_waitcnt lgkmcnt(0)
	s_setprio 1
	s_waitcnt lgkmcnt(0)
	v_mfma_f32_16x16x32_bf16 v[94:97], v[130:133], v[206:209], v[94:97]
	v_mfma_f32_16x16x32_bf16 v[90:93], v[150:153], v[206:209], v[90:93]
	s_barrier
	v_mfma_f32_16x16x32_bf16 v[86:89], v[130:133], v[214:217], v[86:89]
	v_mfma_f32_16x16x32_bf16 v[82:85], v[150:153], v[214:217], v[82:85]
	v_mfma_f32_16x16x32_bf16 v[78:81], v[130:133], v[222:225], v[78:81]
	v_mfma_f32_16x16x32_bf16 v[74:77], v[150:153], v[222:225], v[74:77]
	v_mfma_f32_16x16x32_bf16 v[70:73], v[130:133], v[230:233], v[70:73]
	v_mfma_f32_16x16x32_bf16 v[62:65], v[150:153], v[230:233], v[62:65]
	v_mfma_f32_16x16x32_bf16 v[94:97], v[134:137], v[210:213], v[94:97]
	v_mfma_f32_16x16x32_bf16 v[90:93], v[156:159], v[210:213], v[90:93]
	v_mfma_f32_16x16x32_bf16 v[86:89], v[134:137], v[218:221], v[86:89]
	v_mfma_f32_16x16x32_bf16 v[82:85], v[156:159], v[218:221], v[82:85]
	v_mfma_f32_16x16x32_bf16 v[78:81], v[134:137], v[226:229], v[78:81]
	v_mfma_f32_16x16x32_bf16 v[74:77], v[156:159], v[226:229], v[74:77]
	v_mfma_f32_16x16x32_bf16 v[70:73], v[134:137], v[234:237], v[70:73]
	v_mfma_f32_16x16x32_bf16 v[62:65], v[156:159], v[234:237], v[62:65]
	v_mfma_f32_16x16x32_bf16 v[30:33], v[160:163], v[206:209], v[30:33]
	v_mfma_f32_16x16x32_bf16 v[26:29], v[182:185], v[206:209], v[26:29]
	v_mfma_f32_16x16x32_bf16 v[22:25], v[160:163], v[214:217], v[22:25]
	v_mfma_f32_16x16x32_bf16 v[18:21], v[182:185], v[214:217], v[18:21]
	v_mfma_f32_16x16x32_bf16 v[14:17], v[160:163], v[222:225], v[14:17]
	v_mfma_f32_16x16x32_bf16 v[10:13], v[182:185], v[222:225], v[10:13]
	v_mfma_f32_16x16x32_bf16 v[6:9], v[160:163], v[230:233], v[6:9]
	v_mfma_f32_16x16x32_bf16 v[2:5], v[182:185], v[230:233], v[2:5]
	v_mfma_f32_16x16x32_bf16 v[30:33], v[178:181], v[210:213], v[30:33]
	v_mfma_f32_16x16x32_bf16 v[26:29], v[186:189], v[210:213], v[26:29]
	v_mfma_f32_16x16x32_bf16 v[22:25], v[178:181], v[218:221], v[22:25]
	v_mfma_f32_16x16x32_bf16 v[18:21], v[186:189], v[218:221], v[18:21]
	v_mfma_f32_16x16x32_bf16 v[14:17], v[178:181], v[226:229], v[14:17]
	v_mfma_f32_16x16x32_bf16 v[10:13], v[186:189], v[226:229], v[10:13]
	v_mfma_f32_16x16x32_bf16 v[6:9], v[178:181], v[234:237], v[6:9]
	v_mfma_f32_16x16x32_bf16 v[2:5], v[186:189], v[234:237], v[2:5]
	s_barrier
	s_setprio 0
	s_add_i32 s48, 0, 0x18000
	s_add_i32 s49, 0, 0x1c000
	v_add_u32_e32 v156, s48, v1
	v_add_u32_e32 v186, s49, v1
	ds_read_b128 v[130:133], v156
	ds_read_b128 v[134:137], v156 offset:1024
	ds_read_b128 v[150:153], v156 offset:2048
	ds_read_b128 v[156:159], v156 offset:3072
	ds_read_b128 v[160:163], v186
	ds_read_b128 v[178:181], v186 offset:1024
	ds_read_b128 v[182:185], v186 offset:2048
	ds_read_b128 v[186:189], v186 offset:3072
	s_add_u32 s46, s70, 0x80000
	s_addc_u32 s47, s71, 0
	s_mov_b32 m0, s79
	v_lshl_add_u64 v[248:249], s[46:47], 0, v[138:139]
	ds_read_b128 v[206:209], v155 offset:32768
	ds_read_b128 v[210:213], v155 offset:33792
	ds_read_b128 v[214:217], v155 offset:34816
	ds_read_b128 v[218:221], v155 offset:35840
	ds_read_b128 v[222:225], v155 offset:36864
	ds_read_b128 v[226:229], v155 offset:37888
	ds_read_b128 v[230:233], v155 offset:38912
	ds_read_b128 v[234:237], v155 offset:39936
	global_load_lds_dwordx4 v[248:249], off
	v_lshl_add_u64 v[248:249], s[46:47], 0, v[140:141]
	s_mov_b32 m0, s80
	s_nop 0
	global_load_lds_dwordx4 v[248:249], off
	s_waitcnt vmcnt(8)
	s_waitcnt lgkmcnt(0)
	s_setprio 1
	s_waitcnt lgkmcnt(0)
	v_mfma_f32_16x16x32_bf16 v[126:129], v[130:133], v[206:209], v[126:129]
	v_mfma_f32_16x16x32_bf16 v[122:125], v[150:153], v[206:209], v[122:125]
	v_mfma_f32_16x16x32_bf16 v[118:121], v[130:133], v[214:217], v[118:121]
	v_mfma_f32_16x16x32_bf16 v[114:117], v[150:153], v[214:217], v[114:117]
	s_barrier
	v_mfma_f32_16x16x32_bf16 v[110:113], v[130:133], v[222:225], v[110:113]
	v_mfma_f32_16x16x32_bf16 v[106:109], v[150:153], v[222:225], v[106:109]
	v_mfma_f32_16x16x32_bf16 v[102:105], v[130:133], v[230:233], v[102:105]
	v_mfma_f32_16x16x32_bf16 v[98:101], v[150:153], v[230:233], v[98:101]
	v_mfma_f32_16x16x32_bf16 v[126:129], v[134:137], v[210:213], v[126:129]
	v_mfma_f32_16x16x32_bf16 v[122:125], v[156:159], v[210:213], v[122:125]
	v_mfma_f32_16x16x32_bf16 v[118:121], v[134:137], v[218:221], v[118:121]
	v_mfma_f32_16x16x32_bf16 v[114:117], v[156:159], v[218:221], v[114:117]
	v_mfma_f32_16x16x32_bf16 v[110:113], v[134:137], v[226:229], v[110:113]
	v_mfma_f32_16x16x32_bf16 v[106:109], v[156:159], v[226:229], v[106:109]
	v_mfma_f32_16x16x32_bf16 v[102:105], v[134:137], v[234:237], v[102:105]
	v_mfma_f32_16x16x32_bf16 v[98:101], v[156:159], v[234:237], v[98:101]
	v_mfma_f32_16x16x32_bf16 v[66:69], v[160:163], v[206:209], v[66:69]
	v_mfma_f32_16x16x32_bf16 v[58:61], v[182:185], v[206:209], v[58:61]
	v_mfma_f32_16x16x32_bf16 v[54:57], v[160:163], v[214:217], v[54:57]
	v_mfma_f32_16x16x32_bf16 v[50:53], v[182:185], v[214:217], v[50:53]
	v_mfma_f32_16x16x32_bf16 v[46:49], v[160:163], v[222:225], v[46:49]
	v_mfma_f32_16x16x32_bf16 v[42:45], v[182:185], v[222:225], v[42:45]
	v_mfma_f32_16x16x32_bf16 v[38:41], v[160:163], v[230:233], v[38:41]
	v_mfma_f32_16x16x32_bf16 v[34:37], v[182:185], v[230:233], v[34:37]
	v_mfma_f32_16x16x32_bf16 v[66:69], v[178:181], v[210:213], v[66:69]
	v_mfma_f32_16x16x32_bf16 v[58:61], v[186:189], v[210:213], v[58:61]
	v_mfma_f32_16x16x32_bf16 v[54:57], v[178:181], v[218:221], v[54:57]
	v_mfma_f32_16x16x32_bf16 v[50:53], v[186:189], v[218:221], v[50:53]
	v_mfma_f32_16x16x32_bf16 v[46:49], v[178:181], v[226:229], v[46:49]
	v_mfma_f32_16x16x32_bf16 v[42:45], v[186:189], v[226:229], v[42:45]
	v_mfma_f32_16x16x32_bf16 v[38:41], v[178:181], v[234:237], v[38:41]
	v_mfma_f32_16x16x32_bf16 v[34:37], v[186:189], v[234:237], v[34:37]
	s_barrier
	s_setprio 0
	s_add_i32 s46, s48, s77
	v_lshl_add_u64 v[164:165], v[164:165], 0, s[42:43]
	s_mov_b32 m0, s46
	ds_read_b128 v[206:209], v155 offset:49152
	ds_read_b128 v[210:213], v155 offset:50176
	ds_read_b128 v[214:217], v155 offset:51200
	ds_read_b128 v[218:221], v155 offset:52224
	ds_read_b128 v[222:225], v155 offset:53248
	ds_read_b128 v[226:229], v155 offset:54272
	ds_read_b128 v[230:233], v155 offset:55296
	ds_read_b128 v[234:237], v155 offset:56320
	global_load_lds_dwordx4 v[164:165], off
	s_add_i32 m0, s46, 0x2000
	s_add_u32 s46, s60, 0x80080
	v_lshl_add_u64 v[164:165], v[242:243], 0, s[42:43]
	s_addc_u32 s47, s61, 0
	s_add_i32 s48, s49, s77
	global_load_lds_dwordx4 v[164:165], off
	v_lshl_add_u64 v[164:165], s[46:47], 0, v[166:167]
	s_mov_b32 m0, s48
	s_nop 0
	global_load_lds_dwordx4 v[164:165], off
	v_lshl_add_u64 v[164:165], s[46:47], 0, v[142:143]
	s_add_i32 m0, s48, 0x2000
	s_nop 0
	global_load_lds_dwordx4 v[164:165], off
	v_lshl_add_u64 v[164:165], v[244:245], 0, s[42:43]
	s_mov_b32 m0, s26
	s_nop 0
	global_load_lds_dwordx4 v[164:165], off
	v_lshl_add_u64 v[164:165], v[246:247], 0, s[42:43]
	s_mov_b32 m0, s81
	s_nop 0
	global_load_lds_dwordx4 v[164:165], off
	s_waitcnt vmcnt(8)
	s_waitcnt lgkmcnt(0)
	s_setprio 1
	s_waitcnt lgkmcnt(0)
	v_mfma_f32_16x16x32_bf16 v[94:97], v[130:133], v[206:209], v[94:97]
	v_mfma_f32_16x16x32_bf16 v[90:93], v[150:153], v[206:209], v[90:93]
	s_barrier
	v_mfma_f32_16x16x32_bf16 v[86:89], v[130:133], v[214:217], v[86:89]
	v_mfma_f32_16x16x32_bf16 v[82:85], v[150:153], v[214:217], v[82:85]
	v_mfma_f32_16x16x32_bf16 v[78:81], v[130:133], v[222:225], v[78:81]
	v_mfma_f32_16x16x32_bf16 v[74:77], v[150:153], v[222:225], v[74:77]
	v_mfma_f32_16x16x32_bf16 v[70:73], v[130:133], v[230:233], v[70:73]
	v_mfma_f32_16x16x32_bf16 v[62:65], v[150:153], v[230:233], v[62:65]
	v_mfma_f32_16x16x32_bf16 v[94:97], v[134:137], v[210:213], v[94:97]
	v_mfma_f32_16x16x32_bf16 v[90:93], v[156:159], v[210:213], v[90:93]
	v_mfma_f32_16x16x32_bf16 v[86:89], v[134:137], v[218:221], v[86:89]
	v_mfma_f32_16x16x32_bf16 v[82:85], v[156:159], v[218:221], v[82:85]
	v_mfma_f32_16x16x32_bf16 v[78:81], v[134:137], v[226:229], v[78:81]
	v_mfma_f32_16x16x32_bf16 v[74:77], v[156:159], v[226:229], v[74:77]
	v_mfma_f32_16x16x32_bf16 v[70:73], v[134:137], v[234:237], v[70:73]
	v_mfma_f32_16x16x32_bf16 v[62:65], v[156:159], v[234:237], v[62:65]
	v_mfma_f32_16x16x32_bf16 v[30:33], v[160:163], v[206:209], v[30:33]
	v_mfma_f32_16x16x32_bf16 v[26:29], v[182:185], v[206:209], v[26:29]
	v_mfma_f32_16x16x32_bf16 v[22:25], v[160:163], v[214:217], v[22:25]
	v_mfma_f32_16x16x32_bf16 v[18:21], v[182:185], v[214:217], v[18:21]
	v_mfma_f32_16x16x32_bf16 v[14:17], v[160:163], v[222:225], v[14:17]
	v_mfma_f32_16x16x32_bf16 v[10:13], v[182:185], v[222:225], v[10:13]
	v_mfma_f32_16x16x32_bf16 v[6:9], v[160:163], v[230:233], v[6:9]
	v_mfma_f32_16x16x32_bf16 v[2:5], v[182:185], v[230:233], v[2:5]
	v_mfma_f32_16x16x32_bf16 v[30:33], v[178:181], v[210:213], v[30:33]
	v_mfma_f32_16x16x32_bf16 v[26:29], v[186:189], v[210:213], v[26:29]
	v_mfma_f32_16x16x32_bf16 v[22:25], v[178:181], v[218:221], v[22:25]
	v_mfma_f32_16x16x32_bf16 v[18:21], v[186:189], v[218:221], v[18:21]
	v_mfma_f32_16x16x32_bf16 v[14:17], v[178:181], v[226:229], v[14:17]
	v_mfma_f32_16x16x32_bf16 v[10:13], v[186:189], v[226:229], v[10:13]
	v_mfma_f32_16x16x32_bf16 v[6:9], v[178:181], v[234:237], v[6:9]
	v_mfma_f32_16x16x32_bf16 v[2:5], v[186:189], v[234:237], v[2:5]
	s_barrier
	s_setprio 0
	s_add_i32 s87, s87, 2
	s_add_u32 s68, s68, 0x100
	s_addc_u32 s69, s69, 0
	s_add_u32 s85, s85, 0x100
	s_addc_u32 s86, s86, 0
	s_cmp_gt_u32 s87, 29
	s_cbranch_scc0 .LBB0_795
	s_and_b64 vcc, exec, s[12:13]
	s_cbranch_vccz .LBB0_798
	s_barrier

.LBB0_819:
	s_add_i32 s93, s60, 2
	s_add_u32 s46, s72, 0x80
	s_addc_u32 s47, s73, 0
	s_add_i32 s48, 0, 0x10000
	s_cmp_eq_u32 s87, s60
	s_cselect_b32 s61, s23, s47
	s_cselect_b32 s60, s64, s46
	s_cselect_b32 s47, s21, s92
	s_cselect_b32 s46, s90, s91
	s_add_i32 s49, 0, 0x14000
	v_add_u32_e32 v142, s48, v205
	v_add_u32_e32 v182, s49, v205
	ds_read_b128 v[130:133], v142
	ds_read_b128 v[134:137], v142 offset:1024
	ds_read_b128 v[138:141], v142 offset:2048
	ds_read_b128 v[142:145], v142 offset:3072
	ds_read_b128 v[146:149], v182
	ds_read_b128 v[150:153], v182 offset:1024
	ds_read_b128 v[178:181], v182 offset:2048
	ds_read_b128 v[182:185], v182 offset:3072
	v_lshl_add_u64 v[236:237], s[72:73], 0, v[162:163]
	s_add_i32 m0, s71, 0xc000
	ds_read_b128 v[186:189], v207
	ds_read_b128 v[208:211], v207 offset:1024
	ds_read_b128 v[212:215], v207 offset:2048
	ds_read_b128 v[216:219], v207 offset:3072
	ds_read_b128 v[220:223], v207 offset:4096
	ds_read_b128 v[224:227], v207 offset:5120
	ds_read_b128 v[228:231], v207 offset:6144
	ds_read_b128 v[232:235], v207 offset:7168
	global_load_lds_dwordx4 v[236:237], off
	v_lshl_add_u64 v[236:237], s[72:73], 0, v[164:165]
	s_add_i32 m0, s71, 0xe000
	s_nop 0
	global_load_lds_dwordx4 v[236:237], off
	s_waitcnt vmcnt(8)
	s_waitcnt lgkmcnt(0)
	s_setprio 1
	s_waitcnt lgkmcnt(0)
	v_mfma_f32_16x16x32_bf16 v[126:129], v[130:133], v[186:189], v[126:129]
	v_mfma_f32_16x16x32_bf16 v[122:125], v[138:141], v[186:189], v[122:125]
	v_mfma_f32_16x16x32_bf16 v[118:121], v[130:133], v[212:215], v[118:121]
	v_mfma_f32_16x16x32_bf16 v[114:117], v[138:141], v[212:215], v[114:117]
	s_barrier
	v_mfma_f32_16x16x32_bf16 v[110:113], v[130:133], v[220:223], v[110:113]
	v_mfma_f32_16x16x32_bf16 v[106:109], v[138:141], v[220:223], v[106:109]
	v_mfma_f32_16x16x32_bf16 v[102:105], v[130:133], v[228:231], v[102:105]
	v_mfma_f32_16x16x32_bf16 v[98:101], v[138:141], v[228:231], v[98:101]
	v_mfma_f32_16x16x32_bf16 v[126:129], v[134:137], v[208:211], v[126:129]
	v_mfma_f32_16x16x32_bf16 v[122:125], v[142:145], v[208:211], v[122:125]
	v_mfma_f32_16x16x32_bf16 v[118:121], v[134:137], v[216:219], v[118:121]
	v_mfma_f32_16x16x32_bf16 v[114:117], v[142:145], v[216:219], v[114:117]
	v_mfma_f32_16x16x32_bf16 v[110:113], v[134:137], v[224:227], v[110:113]
	v_mfma_f32_16x16x32_bf16 v[106:109], v[142:145], v[224:227], v[106:109]
	v_mfma_f32_16x16x32_bf16 v[102:105], v[134:137], v[232:235], v[102:105]
	v_mfma_f32_16x16x32_bf16 v[98:101], v[142:145], v[232:235], v[98:101]
	v_mfma_f32_16x16x32_bf16 v[94:97], v[146:149], v[186:189], v[94:97]
	v_mfma_f32_16x16x32_bf16 v[90:93], v[178:181], v[186:189], v[90:93]
	v_mfma_f32_16x16x32_bf16 v[86:89], v[146:149], v[212:215], v[86:89]
	v_mfma_f32_16x16x32_bf16 v[82:85], v[178:181], v[212:215], v[82:85]
	v_mfma_f32_16x16x32_bf16 v[78:81], v[146:149], v[220:223], v[78:81]
	v_mfma_f32_16x16x32_bf16 v[74:77], v[178:181], v[220:223], v[74:77]
	v_mfma_f32_16x16x32_bf16 v[70:73], v[146:149], v[228:231], v[70:73]
	v_mfma_f32_16x16x32_bf16 v[66:69], v[178:181], v[228:231], v[66:69]
	v_mfma_f32_16x16x32_bf16 v[94:97], v[150:153], v[208:211], v[94:97]
	v_mfma_f32_16x16x32_bf16 v[90:93], v[182:185], v[208:211], v[90:93]
	v_mfma_f32_16x16x32_bf16 v[86:89], v[150:153], v[216:219], v[86:89]
	v_mfma_f32_16x16x32_bf16 v[82:85], v[182:185], v[216:219], v[82:85]
	v_mfma_f32_16x16x32_bf16 v[78:81], v[150:153], v[224:227], v[78:81]
	v_mfma_f32_16x16x32_bf16 v[74:77], v[182:185], v[224:227], v[74:77]
	v_mfma_f32_16x16x32_bf16 v[70:73], v[150:153], v[232:235], v[70:73]
	v_mfma_f32_16x16x32_bf16 v[66:69], v[182:185], v[232:235], v[66:69]
	s_barrier
	s_setprio 0
	s_add_i32 s48, s48, s80
	v_lshl_add_u64 v[236:237], s[46:47], 0, v[166:167]
	s_mov_b32 m0, s48
	ds_read_b128 v[186:189], v207 offset:16384
	ds_read_b128 v[208:211], v207 offset:17408
	ds_read_b128 v[212:215], v207 offset:18432
	ds_read_b128 v[216:219], v207 offset:19456
	ds_read_b128 v[220:223], v207 offset:20480
	ds_read_b128 v[224:227], v207 offset:21504
	ds_read_b128 v[228:231], v207 offset:22528
	ds_read_b128 v[232:235], v207 offset:23552
	global_load_lds_dwordx4 v[236:237], off
	s_add_i32 m0, s48, 0x2000
	v_lshl_add_u64 v[242:243], s[46:47], 0, v[158:159]
	s_add_u32 s46, s46, s26
	s_addc_u32 s47, s47, 0
	s_add_i32 s48, s49, s80
	global_load_lds_dwordx4 v[242:243], off
	v_lshl_add_u64 v[244:245], s[46:47], 0, v[166:167]
	s_mov_b32 m0, s48
	v_lshl_add_u64 v[246:247], s[46:47], 0, v[158:159]
	global_load_lds_dwordx4 v[244:245], off
	s_add_i32 m0, s48, 0x2000
	v_lshl_add_u64 v[248:249], s[60:61], 0, v[154:155]
	global_load_lds_dwordx4 v[246:247], off
	s_mov_b32 m0, s71
	v_lshl_add_u64 v[250:251], s[60:61], 0, v[156:157]
	global_load_lds_dwordx4 v[248:249], off
	s_mov_b32 m0, s81
	s_nop 0
	global_load_lds_dwordx4 v[250:251], off
	s_waitcnt vmcnt(8)
	s_waitcnt lgkmcnt(0)
	s_setprio 1
	s_waitcnt lgkmcnt(0)
	v_mfma_f32_16x16x32_bf16 v[62:65], v[130:133], v[186:189], v[62:65]
	v_mfma_f32_16x16x32_bf16 v[58:61], v[138:141], v[186:189], v[58:61]
	s_barrier
	v_mfma_f32_16x16x32_bf16 v[54:57], v[130:133], v[212:215], v[54:57]
	v_mfma_f32_16x16x32_bf16 v[50:53], v[138:141], v[212:215], v[50:53]
	v_mfma_f32_16x16x32_bf16 v[46:49], v[130:133], v[220:223], v[46:49]
	v_mfma_f32_16x16x32_bf16 v[42:45], v[138:141], v[220:223], v[42:45]
	v_mfma_f32_16x16x32_bf16 v[38:41], v[130:133], v[228:231], v[38:41]
	v_mfma_f32_16x16x32_bf16 v[34:37], v[138:141], v[228:231], v[34:37]
	v_mfma_f32_16x16x32_bf16 v[62:65], v[134:137], v[208:211], v[62:65]
	v_mfma_f32_16x16x32_bf16 v[58:61], v[142:145], v[208:211], v[58:61]
	v_mfma_f32_16x16x32_bf16 v[54:57], v[134:137], v[216:219], v[54:57]
	v_mfma_f32_16x16x32_bf16 v[50:53], v[142:145], v[216:219], v[50:53]
	v_mfma_f32_16x16x32_bf16 v[46:49], v[134:137], v[224:227], v[46:49]
	v_mfma_f32_16x16x32_bf16 v[42:45], v[142:145], v[224:227], v[42:45]
	v_mfma_f32_16x16x32_bf16 v[38:41], v[134:137], v[232:235], v[38:41]
	v_mfma_f32_16x16x32_bf16 v[34:37], v[142:145], v[232:235], v[34:37]
	v_mfma_f32_16x16x32_bf16 v[30:33], v[146:149], v[186:189], v[30:33]
	v_mfma_f32_16x16x32_bf16 v[26:29], v[178:181], v[186:189], v[26:29]
	v_mfma_f32_16x16x32_bf16 v[22:25], v[146:149], v[212:215], v[22:25]
	v_mfma_f32_16x16x32_bf16 v[18:21], v[178:181], v[212:215], v[18:21]
	v_mfma_f32_16x16x32_bf16 v[14:17], v[146:149], v[220:223], v[14:17]
	v_mfma_f32_16x16x32_bf16 v[10:13], v[178:181], v[220:223], v[10:13]
	v_mfma_f32_16x16x32_bf16 v[6:9], v[146:149], v[228:231], v[6:9]
	v_mfma_f32_16x16x32_bf16 v[2:5], v[178:181], v[228:231], v[2:5]
	v_mfma_f32_16x16x32_bf16 v[30:33], v[150:153], v[208:211], v[30:33]
	v_mfma_f32_16x16x32_bf16 v[26:29], v[182:185], v[208:211], v[26:29]
	v_mfma_f32_16x16x32_bf16 v[22:25], v[150:153], v[216:219], v[22:25]
	v_mfma_f32_16x16x32_bf16 v[18:21], v[182:185], v[216:219], v[18:21]
	v_mfma_f32_16x16x32_bf16 v[14:17], v[150:153], v[224:227], v[14:17]
	v_mfma_f32_16x16x32_bf16 v[10:13], v[182:185], v[224:227], v[10:13]
	v_mfma_f32_16x16x32_bf16 v[6:9], v[150:153], v[232:235], v[6:9]
	v_mfma_f32_16x16x32_bf16 v[2:5], v[182:185], v[232:235], v[2:5]
	s_barrier
	s_setprio 0
	s_add_i32 s48, 0, 0x18000
	s_add_i32 s49, 0, 0x1c000
	v_add_u32_e32 v142, s48, v205
	v_add_u32_e32 v182, s49, v205
	ds_read_b128 v[130:133], v142
	ds_read_b128 v[134:137], v142 offset:1024
	ds_read_b128 v[138:141], v142 offset:2048
	ds_read_b128 v[142:145], v142 offset:3072
	ds_read_b128 v[146:149], v182
	ds_read_b128 v[150:153], v182 offset:1024
	ds_read_b128 v[178:181], v182 offset:2048
	ds_read_b128 v[182:185], v182 offset:3072
	s_add_u32 s46, s60, s26
	s_addc_u32 s47, s61, 0
	s_mov_b32 m0, s82
	v_lshl_add_u64 v[252:253], s[46:47], 0, v[154:155]
	ds_read_b128 v[186:189], v207 offset:32768
	ds_read_b128 v[208:211], v207 offset:33792
	ds_read_b128 v[212:215], v207 offset:34816
	ds_read_b128 v[216:219], v207 offset:35840
	ds_read_b128 v[220:223], v207 offset:36864
	ds_read_b128 v[224:227], v207 offset:37888
	ds_read_b128 v[228:231], v207 offset:38912
	ds_read_b128 v[232:235], v207 offset:39936
	global_load_lds_dwordx4 v[252:253], off
	v_lshl_add_u64 v[252:253], s[46:47], 0, v[156:157]
	s_mov_b32 m0, s83
	s_nop 0
	global_load_lds_dwordx4 v[252:253], off
	s_waitcnt vmcnt(8)
	s_waitcnt lgkmcnt(0)
	s_setprio 1
	s_waitcnt lgkmcnt(0)
	v_mfma_f32_16x16x32_bf16 v[126:129], v[130:133], v[186:189], v[126:129]
	v_mfma_f32_16x16x32_bf16 v[122:125], v[138:141], v[186:189], v[122:125]
	v_mfma_f32_16x16x32_bf16 v[118:121], v[130:133], v[212:215], v[118:121]
	v_mfma_f32_16x16x32_bf16 v[114:117], v[138:141], v[212:215], v[114:117]
	s_barrier
	v_mfma_f32_16x16x32_bf16 v[110:113], v[130:133], v[220:223], v[110:113]
	v_mfma_f32_16x16x32_bf16 v[106:109], v[138:141], v[220:223], v[106:109]
	v_mfma_f32_16x16x32_bf16 v[102:105], v[130:133], v[228:231], v[102:105]
	v_mfma_f32_16x16x32_bf16 v[98:101], v[138:141], v[228:231], v[98:101]
	v_mfma_f32_16x16x32_bf16 v[126:129], v[134:137], v[208:211], v[126:129]
	v_mfma_f32_16x16x32_bf16 v[122:125], v[142:145], v[208:211], v[122:125]
	v_mfma_f32_16x16x32_bf16 v[118:121], v[134:137], v[216:219], v[118:121]
	v_mfma_f32_16x16x32_bf16 v[114:117], v[142:145], v[216:219], v[114:117]
	v_mfma_f32_16x16x32_bf16 v[110:113], v[134:137], v[224:227], v[110:113]
	v_mfma_f32_16x16x32_bf16 v[106:109], v[142:145], v[224:227], v[106:109]
	v_mfma_f32_16x16x32_bf16 v[102:105], v[134:137], v[232:235], v[102:105]
	v_mfma_f32_16x16x32_bf16 v[98:101], v[142:145], v[232:235], v[98:101]
	v_mfma_f32_16x16x32_bf16 v[94:97], v[146:149], v[186:189], v[94:97]
	v_mfma_f32_16x16x32_bf16 v[90:93], v[178:181], v[186:189], v[90:93]
	v_mfma_f32_16x16x32_bf16 v[86:89], v[146:149], v[212:215], v[86:89]
	v_mfma_f32_16x16x32_bf16 v[82:85], v[178:181], v[212:215], v[82:85]
	v_mfma_f32_16x16x32_bf16 v[78:81], v[146:149], v[220:223], v[78:81]
	v_mfma_f32_16x16x32_bf16 v[74:77], v[178:181], v[220:223], v[74:77]
	v_mfma_f32_16x16x32_bf16 v[70:73], v[146:149], v[228:231], v[70:73]
	v_mfma_f32_16x16x32_bf16 v[66:69], v[178:181], v[228:231], v[66:69]
	v_mfma_f32_16x16x32_bf16 v[94:97], v[150:153], v[208:211], v[94:97]
	v_mfma_f32_16x16x32_bf16 v[90:93], v[182:185], v[208:211], v[90:93]
	v_mfma_f32_16x16x32_bf16 v[86:89], v[150:153], v[216:219], v[86:89]
	v_mfma_f32_16x16x32_bf16 v[82:85], v[182:185], v[216:219], v[82:85]
	v_mfma_f32_16x16x32_bf16 v[78:81], v[150:153], v[224:227], v[78:81]
	v_mfma_f32_16x16x32_bf16 v[74:77], v[182:185], v[224:227], v[74:77]
	v_mfma_f32_16x16x32_bf16 v[70:73], v[150:153], v[232:235], v[70:73]
	v_mfma_f32_16x16x32_bf16 v[66:69], v[182:185], v[232:235], v[66:69]
	s_barrier
	s_setprio 0
	s_add_i32 s46, s48, s80
	v_lshl_add_u64 v[236:237], v[236:237], 0, s[42:43]
	s_mov_b32 m0, s46
	ds_read_b128 v[186:189], v207 offset:49152
	ds_read_b128 v[208:211], v207 offset:50176
	ds_read_b128 v[212:215], v207 offset:51200
	ds_read_b128 v[216:219], v207 offset:52224
	ds_read_b128 v[220:223], v207 offset:53248
	ds_read_b128 v[224:227], v207 offset:54272
	ds_read_b128 v[228:231], v207 offset:55296
	ds_read_b128 v[232:235], v207 offset:56320
	global_load_lds_dwordx4 v[236:237], off
	v_lshl_add_u64 v[236:237], v[242:243], 0, s[42:43]
	s_add_i32 m0, s46, 0x2000
	s_add_i32 s46, s49, s80
	global_load_lds_dwordx4 v[236:237], off
	v_lshl_add_u64 v[236:237], v[244:245], 0, s[42:43]
	s_mov_b32 m0, s46
	s_nop 0
	global_load_lds_dwordx4 v[236:237], off
	v_lshl_add_u64 v[236:237], v[246:247], 0, s[42:43]
	s_add_i32 m0, s46, 0x2000
	s_nop 0
	global_load_lds_dwordx4 v[236:237], off
	v_lshl_add_u64 v[236:237], v[248:249], 0, s[42:43]
	s_mov_b32 m0, s85
	s_nop 0
	global_load_lds_dwordx4 v[236:237], off
	v_lshl_add_u64 v[236:237], v[250:251], 0, s[42:43]
	s_mov_b32 m0, s86
	s_nop 0
	global_load_lds_dwordx4 v[236:237], off
	s_waitcnt vmcnt(8)
	s_waitcnt lgkmcnt(0)
	s_setprio 1
	s_waitcnt lgkmcnt(0)
	v_mfma_f32_16x16x32_bf16 v[62:65], v[130:133], v[186:189], v[62:65]
	v_mfma_f32_16x16x32_bf16 v[58:61], v[138:141], v[186:189], v[58:61]
	s_barrier
	v_mfma_f32_16x16x32_bf16 v[54:57], v[130:133], v[212:215], v[54:57]
	v_mfma_f32_16x16x32_bf16 v[50:53], v[138:141], v[212:215], v[50:53]
	v_mfma_f32_16x16x32_bf16 v[46:49], v[130:133], v[220:223], v[46:49]
	v_mfma_f32_16x16x32_bf16 v[42:45], v[138:141], v[220:223], v[42:45]
	v_mfma_f32_16x16x32_bf16 v[38:41], v[130:133], v[228:231], v[38:41]
	v_mfma_f32_16x16x32_bf16 v[34:37], v[138:141], v[228:231], v[34:37]
	v_mfma_f32_16x16x32_bf16 v[62:65], v[134:137], v[208:211], v[62:65]
	v_mfma_f32_16x16x32_bf16 v[58:61], v[142:145], v[208:211], v[58:61]
	v_mfma_f32_16x16x32_bf16 v[54:57], v[134:137], v[216:219], v[54:57]
	v_mfma_f32_16x16x32_bf16 v[50:53], v[142:145], v[216:219], v[50:53]
	v_mfma_f32_16x16x32_bf16 v[46:49], v[134:137], v[224:227], v[46:49]
	v_mfma_f32_16x16x32_bf16 v[42:45], v[142:145], v[224:227], v[42:45]
	v_mfma_f32_16x16x32_bf16 v[38:41], v[134:137], v[232:235], v[38:41]
	v_mfma_f32_16x16x32_bf16 v[34:37], v[142:145], v[232:235], v[34:37]
	v_mfma_f32_16x16x32_bf16 v[30:33], v[146:149], v[186:189], v[30:33]
	v_mfma_f32_16x16x32_bf16 v[26:29], v[178:181], v[186:189], v[26:29]
	v_mfma_f32_16x16x32_bf16 v[22:25], v[146:149], v[212:215], v[22:25]
	v_mfma_f32_16x16x32_bf16 v[18:21], v[178:181], v[212:215], v[18:21]
	v_mfma_f32_16x16x32_bf16 v[14:17], v[146:149], v[220:223], v[14:17]
	v_mfma_f32_16x16x32_bf16 v[10:13], v[178:181], v[220:223], v[10:13]
	v_mfma_f32_16x16x32_bf16 v[6:9], v[146:149], v[228:231], v[6:9]
	v_mfma_f32_16x16x32_bf16 v[2:5], v[178:181], v[228:231], v[2:5]
	v_mfma_f32_16x16x32_bf16 v[30:33], v[150:153], v[208:211], v[30:33]
	v_mfma_f32_16x16x32_bf16 v[26:29], v[182:185], v[208:211], v[26:29]
	v_mfma_f32_16x16x32_bf16 v[22:25], v[150:153], v[216:219], v[22:25]
	v_mfma_f32_16x16x32_bf16 v[18:21], v[182:185], v[216:219], v[18:21]
	v_mfma_f32_16x16x32_bf16 v[14:17], v[150:153], v[224:227], v[14:17]
	v_mfma_f32_16x16x32_bf16 v[10:13], v[182:185], v[224:227], v[10:13]
	v_mfma_f32_16x16x32_bf16 v[6:9], v[150:153], v[232:235], v[6:9]
	v_mfma_f32_16x16x32_bf16 v[2:5], v[182:185], v[232:235], v[2:5]
	s_barrier
	s_setprio 0
	s_add_u32 s72, s72, 0x100
	s_addc_u32 s73, s73, 0
	s_add_u32 s91, s91, 0x100
	s_addc_u32 s92, s92, 0
	s_cmp_ge_u32 s93, s84
	s_mov_b32 s60, s93
	s_cbranch_scc0 .LBB0_819
	s_and_b64 vcc, exec, s[18:19]
	s_cbranch_vccz .LBB0_822
	s_barrier

.LBB0_903:
	s_add_u32 s46, s66, 0xfff80080
	s_addc_u32 s47, s67, -1
	s_add_i32 s48, 0, 0x10000
	s_cmp_eq_u32 s84, 28
	s_cselect_b32 s69, s17, s47
	s_cselect_b32 s68, s64, s46
	s_cselect_b32 s61, s13, s83
	s_cselect_b32 s60, s81, s82
	s_add_i32 s49, 0, 0x14000
	v_add_u32_e32 v142, s48, v186
	v_add_u32_e32 v164, s49, v186
	ds_read_b128 v[130:133], v142
	ds_read_b128 v[134:137], v142 offset:1024
	ds_read_b128 v[138:141], v142 offset:2048
	ds_read_b128 v[142:145], v142 offset:3072
	ds_read_b128 v[146:149], v164
	ds_read_b128 v[160:163], v164 offset:1024
	ds_read_b128 v[178:181], v164 offset:2048
	ds_read_b128 v[182:185], v164 offset:3072
	v_lshl_add_u64 v[164:165], s[66:67], 0, v[156:157]
	s_add_i32 m0, s74, 0xc000
	ds_read_b128 v[206:209], v188
	ds_read_b128 v[210:213], v188 offset:1024
	ds_read_b128 v[214:217], v188 offset:2048
	ds_read_b128 v[218:221], v188 offset:3072
	ds_read_b128 v[222:225], v188 offset:4096
	ds_read_b128 v[226:229], v188 offset:5120
	ds_read_b128 v[230:233], v188 offset:6144
	ds_read_b128 v[234:237], v188 offset:7168
	global_load_lds_dwordx4 v[164:165], off
	v_lshl_add_u64 v[164:165], s[66:67], 0, v[158:159]
	s_add_i32 m0, s74, 0xe000
	s_nop 0
	global_load_lds_dwordx4 v[164:165], off
	s_waitcnt vmcnt(8)
	s_waitcnt lgkmcnt(0)
	s_setprio 1
	s_waitcnt lgkmcnt(0)
	v_mfma_f32_16x16x32_bf16 v[126:129], v[130:133], v[206:209], v[126:129]
	v_mfma_f32_16x16x32_bf16 v[122:125], v[138:141], v[206:209], v[122:125]
	v_mfma_f32_16x16x32_bf16 v[118:121], v[130:133], v[214:217], v[118:121]
	v_mfma_f32_16x16x32_bf16 v[110:113], v[138:141], v[214:217], v[110:113]
	s_barrier
	v_mfma_f32_16x16x32_bf16 v[94:97], v[130:133], v[222:225], v[94:97]
	v_mfma_f32_16x16x32_bf16 v[90:93], v[138:141], v[222:225], v[90:93]
	v_mfma_f32_16x16x32_bf16 v[82:85], v[130:133], v[230:233], v[82:85]
	v_mfma_f32_16x16x32_bf16 v[74:77], v[138:141], v[230:233], v[74:77]
	v_mfma_f32_16x16x32_bf16 v[126:129], v[134:137], v[210:213], v[126:129]
	v_mfma_f32_16x16x32_bf16 v[122:125], v[142:145], v[210:213], v[122:125]
	v_mfma_f32_16x16x32_bf16 v[118:121], v[134:137], v[218:221], v[118:121]
	v_mfma_f32_16x16x32_bf16 v[110:113], v[142:145], v[218:221], v[110:113]
	v_mfma_f32_16x16x32_bf16 v[94:97], v[134:137], v[226:229], v[94:97]
	v_mfma_f32_16x16x32_bf16 v[90:93], v[142:145], v[226:229], v[90:93]
	v_mfma_f32_16x16x32_bf16 v[82:85], v[134:137], v[234:237], v[82:85]
	v_mfma_f32_16x16x32_bf16 v[74:77], v[142:145], v[234:237], v[74:77]
	v_mfma_f32_16x16x32_bf16 v[114:117], v[146:149], v[206:209], v[114:117]
	v_mfma_f32_16x16x32_bf16 v[106:109], v[178:181], v[206:209], v[106:109]
	v_mfma_f32_16x16x32_bf16 v[102:105], v[146:149], v[214:217], v[102:105]
	v_mfma_f32_16x16x32_bf16 v[98:101], v[178:181], v[214:217], v[98:101]
	v_mfma_f32_16x16x32_bf16 v[86:89], v[146:149], v[222:225], v[86:89]
	v_mfma_f32_16x16x32_bf16 v[78:81], v[178:181], v[222:225], v[78:81]
	v_mfma_f32_16x16x32_bf16 v[70:73], v[146:149], v[230:233], v[70:73]
	v_mfma_f32_16x16x32_bf16 v[66:69], v[178:181], v[230:233], v[66:69]
	v_mfma_f32_16x16x32_bf16 v[114:117], v[160:163], v[210:213], v[114:117]
	v_mfma_f32_16x16x32_bf16 v[106:109], v[182:185], v[210:213], v[106:109]
	v_mfma_f32_16x16x32_bf16 v[102:105], v[160:163], v[218:221], v[102:105]
	v_mfma_f32_16x16x32_bf16 v[98:101], v[182:185], v[218:221], v[98:101]
	v_mfma_f32_16x16x32_bf16 v[86:89], v[160:163], v[226:229], v[86:89]
	v_mfma_f32_16x16x32_bf16 v[78:81], v[182:185], v[226:229], v[78:81]
	v_mfma_f32_16x16x32_bf16 v[70:73], v[160:163], v[234:237], v[70:73]
	v_mfma_f32_16x16x32_bf16 v[66:69], v[182:185], v[234:237], v[66:69]
	s_barrier
	s_setprio 0
	s_add_i32 s46, s48, s73
	v_lshl_add_u64 v[164:165], s[60:61], 0, v[166:167]
	s_mov_b32 m0, s46
	ds_read_b128 v[206:209], v188 offset:16384
	ds_read_b128 v[210:213], v188 offset:17408
	ds_read_b128 v[214:217], v188 offset:18432
	ds_read_b128 v[218:221], v188 offset:19456
	ds_read_b128 v[222:225], v188 offset:20480
	ds_read_b128 v[226:229], v188 offset:21504
	ds_read_b128 v[230:233], v188 offset:22528
	ds_read_b128 v[234:237], v188 offset:23552
	global_load_lds_dwordx4 v[164:165], off
	s_add_i32 m0, s46, 0x2000
	s_add_u32 s46, s60, 0x80000
	v_lshl_add_u64 v[242:243], s[60:61], 0, v[154:155]
	s_addc_u32 s47, s61, 0
	s_add_i32 s48, s49, s73
	global_load_lds_dwordx4 v[242:243], off
	v_lshl_add_u64 v[244:245], s[46:47], 0, v[166:167]
	s_mov_b32 m0, s48
	v_lshl_add_u64 v[246:247], s[68:69], 0, v[152:153]
	global_load_lds_dwordx4 v[244:245], off
	v_lshl_add_u64 v[244:245], s[46:47], 0, v[154:155]
	s_add_i32 m0, s48, 0x2000
	s_nop 0
	global_load_lds_dwordx4 v[244:245], off
	v_lshl_add_u64 v[244:245], s[68:69], 0, v[150:151]
	s_mov_b32 m0, s74
	s_nop 0
	global_load_lds_dwordx4 v[244:245], off
	s_mov_b32 m0, s75
	s_nop 0
	global_load_lds_dwordx4 v[246:247], off
	s_waitcnt vmcnt(8)
	s_waitcnt lgkmcnt(0)
	s_setprio 1
	s_waitcnt lgkmcnt(0)
	v_mfma_f32_16x16x32_bf16 v[62:65], v[130:133], v[206:209], v[62:65]
	v_mfma_f32_16x16x32_bf16 v[58:61], v[138:141], v[206:209], v[58:61]
	s_barrier
	v_mfma_f32_16x16x32_bf16 v[50:53], v[130:133], v[214:217], v[50:53]
	v_mfma_f32_16x16x32_bf16 v[42:45], v[138:141], v[214:217], v[42:45]
	v_mfma_f32_16x16x32_bf16 v[34:37], v[130:133], v[222:225], v[34:37]
	v_mfma_f32_16x16x32_bf16 v[26:29], v[138:141], v[222:225], v[26:29]
	v_mfma_f32_16x16x32_bf16 v[18:21], v[130:133], v[230:233], v[18:21]
	v_mfma_f32_16x16x32_bf16 v[10:13], v[138:141], v[230:233], v[10:13]
	v_mfma_f32_16x16x32_bf16 v[62:65], v[134:137], v[210:213], v[62:65]
	v_mfma_f32_16x16x32_bf16 v[58:61], v[142:145], v[210:213], v[58:61]
	v_mfma_f32_16x16x32_bf16 v[50:53], v[134:137], v[218:221], v[50:53]
	v_mfma_f32_16x16x32_bf16 v[42:45], v[142:145], v[218:221], v[42:45]
	v_mfma_f32_16x16x32_bf16 v[34:37], v[134:137], v[226:229], v[34:37]
	v_mfma_f32_16x16x32_bf16 v[26:29], v[142:145], v[226:229], v[26:29]
	v_mfma_f32_16x16x32_bf16 v[18:21], v[134:137], v[234:237], v[18:21]
	v_mfma_f32_16x16x32_bf16 v[10:13], v[142:145], v[234:237], v[10:13]
	v_mfma_f32_16x16x32_bf16 v[54:57], v[146:149], v[206:209], v[54:57]
	v_mfma_f32_16x16x32_bf16 v[46:49], v[178:181], v[206:209], v[46:49]
	v_mfma_f32_16x16x32_bf16 v[38:41], v[146:149], v[214:217], v[38:41]
	v_mfma_f32_16x16x32_bf16 v[30:33], v[178:181], v[214:217], v[30:33]
	v_mfma_f32_16x16x32_bf16 v[22:25], v[146:149], v[222:225], v[22:25]
	v_mfma_f32_16x16x32_bf16 v[14:17], v[178:181], v[222:225], v[14:17]
	v_mfma_f32_16x16x32_bf16 v[6:9], v[146:149], v[230:233], v[6:9]
	v_mfma_f32_16x16x32_bf16 v[2:5], v[178:181], v[230:233], v[2:5]
	v_mfma_f32_16x16x32_bf16 v[54:57], v[160:163], v[210:213], v[54:57]
	v_mfma_f32_16x16x32_bf16 v[46:49], v[182:185], v[210:213], v[46:49]
	v_mfma_f32_16x16x32_bf16 v[38:41], v[160:163], v[218:221], v[38:41]
	v_mfma_f32_16x16x32_bf16 v[30:33], v[182:185], v[218:221], v[30:33]
	v_mfma_f32_16x16x32_bf16 v[22:25], v[160:163], v[226:229], v[22:25]
	v_mfma_f32_16x16x32_bf16 v[14:17], v[182:185], v[226:229], v[14:17]
	v_mfma_f32_16x16x32_bf16 v[6:9], v[160:163], v[234:237], v[6:9]
	v_mfma_f32_16x16x32_bf16 v[2:5], v[182:185], v[234:237], v[2:5]
	s_barrier
	s_setprio 0
	s_add_i32 s48, 0, 0x18000
	s_add_i32 s49, 0, 0x1c000
	v_add_u32_e32 v142, s48, v186
	v_add_u32_e32 v182, s49, v186
	ds_read_b128 v[130:133], v142
	ds_read_b128 v[134:137], v142 offset:1024
	ds_read_b128 v[138:141], v142 offset:2048
	ds_read_b128 v[142:145], v142 offset:3072
	ds_read_b128 v[146:149], v182
	ds_read_b128 v[160:163], v182 offset:1024
	ds_read_b128 v[178:181], v182 offset:2048
	ds_read_b128 v[182:185], v182 offset:3072
	s_add_u32 s46, s68, 0x80000
	s_addc_u32 s47, s69, 0
	s_mov_b32 m0, s76
	v_lshl_add_u64 v[248:249], s[46:47], 0, v[150:151]
	ds_read_b128 v[206:209], v188 offset:32768
	ds_read_b128 v[210:213], v188 offset:33792
	ds_read_b128 v[214:217], v188 offset:34816
	ds_read_b128 v[218:221], v188 offset:35840
	ds_read_b128 v[222:225], v188 offset:36864
	ds_read_b128 v[226:229], v188 offset:37888
	ds_read_b128 v[230:233], v188 offset:38912
	ds_read_b128 v[234:237], v188 offset:39936
	global_load_lds_dwordx4 v[248:249], off
	v_lshl_add_u64 v[248:249], s[46:47], 0, v[152:153]
	s_mov_b32 m0, s77
	s_nop 0
	global_load_lds_dwordx4 v[248:249], off
	s_waitcnt vmcnt(8)
	s_waitcnt lgkmcnt(0)
	s_setprio 1
	s_waitcnt lgkmcnt(0)
	v_mfma_f32_16x16x32_bf16 v[126:129], v[130:133], v[206:209], v[126:129]
	v_mfma_f32_16x16x32_bf16 v[122:125], v[138:141], v[206:209], v[122:125]
	v_mfma_f32_16x16x32_bf16 v[118:121], v[130:133], v[214:217], v[118:121]
	v_mfma_f32_16x16x32_bf16 v[110:113], v[138:141], v[214:217], v[110:113]
	s_barrier
	v_mfma_f32_16x16x32_bf16 v[94:97], v[130:133], v[222:225], v[94:97]
	v_mfma_f32_16x16x32_bf16 v[90:93], v[138:141], v[222:225], v[90:93]
	v_mfma_f32_16x16x32_bf16 v[82:85], v[130:133], v[230:233], v[82:85]
	v_mfma_f32_16x16x32_bf16 v[74:77], v[138:141], v[230:233], v[74:77]
	v_mfma_f32_16x16x32_bf16 v[126:129], v[134:137], v[210:213], v[126:129]
	v_mfma_f32_16x16x32_bf16 v[122:125], v[142:145], v[210:213], v[122:125]
	v_mfma_f32_16x16x32_bf16 v[118:121], v[134:137], v[218:221], v[118:121]
	v_mfma_f32_16x16x32_bf16 v[110:113], v[142:145], v[218:221], v[110:113]
	v_mfma_f32_16x16x32_bf16 v[94:97], v[134:137], v[226:229], v[94:97]
	v_mfma_f32_16x16x32_bf16 v[90:93], v[142:145], v[226:229], v[90:93]
	v_mfma_f32_16x16x32_bf16 v[82:85], v[134:137], v[234:237], v[82:85]
	v_mfma_f32_16x16x32_bf16 v[74:77], v[142:145], v[234:237], v[74:77]
	v_mfma_f32_16x16x32_bf16 v[114:117], v[146:149], v[206:209], v[114:117]
	v_mfma_f32_16x16x32_bf16 v[106:109], v[178:181], v[206:209], v[106:109]
	v_mfma_f32_16x16x32_bf16 v[102:105], v[146:149], v[214:217], v[102:105]
	v_mfma_f32_16x16x32_bf16 v[98:101], v[178:181], v[214:217], v[98:101]
	v_mfma_f32_16x16x32_bf16 v[86:89], v[146:149], v[222:225], v[86:89]
	v_mfma_f32_16x16x32_bf16 v[78:81], v[178:181], v[222:225], v[78:81]
	v_mfma_f32_16x16x32_bf16 v[70:73], v[146:149], v[230:233], v[70:73]
	v_mfma_f32_16x16x32_bf16 v[66:69], v[178:181], v[230:233], v[66:69]
	v_mfma_f32_16x16x32_bf16 v[114:117], v[160:163], v[210:213], v[114:117]
	v_mfma_f32_16x16x32_bf16 v[106:109], v[182:185], v[210:213], v[106:109]
	v_mfma_f32_16x16x32_bf16 v[102:105], v[160:163], v[218:221], v[102:105]
	v_mfma_f32_16x16x32_bf16 v[98:101], v[182:185], v[218:221], v[98:101]
	v_mfma_f32_16x16x32_bf16 v[86:89], v[160:163], v[226:229], v[86:89]
	v_mfma_f32_16x16x32_bf16 v[78:81], v[182:185], v[226:229], v[78:81]
	v_mfma_f32_16x16x32_bf16 v[70:73], v[160:163], v[234:237], v[70:73]
	v_mfma_f32_16x16x32_bf16 v[66:69], v[182:185], v[234:237], v[66:69]
	s_barrier
	s_setprio 0
	s_add_i32 s46, s48, s73
	v_lshl_add_u64 v[164:165], v[164:165], 0, s[42:43]
	s_mov_b32 m0, s46
	ds_read_b128 v[206:209], v188 offset:49152
	ds_read_b128 v[210:213], v188 offset:50176
	ds_read_b128 v[214:217], v188 offset:51200
	ds_read_b128 v[218:221], v188 offset:52224
	ds_read_b128 v[222:225], v188 offset:53248
	ds_read_b128 v[226:229], v188 offset:54272
	ds_read_b128 v[230:233], v188 offset:55296
	ds_read_b128 v[234:237], v188 offset:56320
	global_load_lds_dwordx4 v[164:165], off
	s_add_i32 m0, s46, 0x2000
	s_add_u32 s46, s60, 0x80080
	v_lshl_add_u64 v[164:165], v[242:243], 0, s[42:43]
	s_addc_u32 s47, s61, 0
	s_add_i32 s48, s49, s73
	global_load_lds_dwordx4 v[164:165], off
	v_lshl_add_u64 v[164:165], s[46:47], 0, v[166:167]
	s_mov_b32 m0, s48
	s_nop 0
	global_load_lds_dwordx4 v[164:165], off
	v_lshl_add_u64 v[164:165], s[46:47], 0, v[154:155]
	s_add_i32 m0, s48, 0x2000
	s_nop 0
	global_load_lds_dwordx4 v[164:165], off
	v_lshl_add_u64 v[164:165], v[244:245], 0, s[42:43]
	s_mov_b32 m0, s78
	s_nop 0
	global_load_lds_dwordx4 v[164:165], off
	v_lshl_add_u64 v[164:165], v[246:247], 0, s[42:43]
	s_mov_b32 m0, s79
	s_nop 0
	global_load_lds_dwordx4 v[164:165], off
	s_waitcnt vmcnt(8)
	s_waitcnt lgkmcnt(0)
	s_setprio 1
	s_waitcnt lgkmcnt(0)
	v_mfma_f32_16x16x32_bf16 v[62:65], v[130:133], v[206:209], v[62:65]
	v_mfma_f32_16x16x32_bf16 v[58:61], v[138:141], v[206:209], v[58:61]
	s_barrier
	v_mfma_f32_16x16x32_bf16 v[50:53], v[130:133], v[214:217], v[50:53]
	v_mfma_f32_16x16x32_bf16 v[42:45], v[138:141], v[214:217], v[42:45]
	v_mfma_f32_16x16x32_bf16 v[34:37], v[130:133], v[222:225], v[34:37]
	v_mfma_f32_16x16x32_bf16 v[26:29], v[138:141], v[222:225], v[26:29]
	v_mfma_f32_16x16x32_bf16 v[18:21], v[130:133], v[230:233], v[18:21]
	v_mfma_f32_16x16x32_bf16 v[10:13], v[138:141], v[230:233], v[10:13]
	v_mfma_f32_16x16x32_bf16 v[62:65], v[134:137], v[210:213], v[62:65]
	v_mfma_f32_16x16x32_bf16 v[58:61], v[142:145], v[210:213], v[58:61]
	v_mfma_f32_16x16x32_bf16 v[50:53], v[134:137], v[218:221], v[50:53]
	v_mfma_f32_16x16x32_bf16 v[42:45], v[142:145], v[218:221], v[42:45]
	v_mfma_f32_16x16x32_bf16 v[34:37], v[134:137], v[226:229], v[34:37]
	v_mfma_f32_16x16x32_bf16 v[26:29], v[142:145], v[226:229], v[26:29]
	v_mfma_f32_16x16x32_bf16 v[18:21], v[134:137], v[234:237], v[18:21]
	v_mfma_f32_16x16x32_bf16 v[10:13], v[142:145], v[234:237], v[10:13]
	v_mfma_f32_16x16x32_bf16 v[54:57], v[146:149], v[206:209], v[54:57]
	v_mfma_f32_16x16x32_bf16 v[46:49], v[178:181], v[206:209], v[46:49]
	v_mfma_f32_16x16x32_bf16 v[38:41], v[146:149], v[214:217], v[38:41]
	v_mfma_f32_16x16x32_bf16 v[30:33], v[178:181], v[214:217], v[30:33]
	v_mfma_f32_16x16x32_bf16 v[22:25], v[146:149], v[222:225], v[22:25]
	v_mfma_f32_16x16x32_bf16 v[14:17], v[178:181], v[222:225], v[14:17]
	v_mfma_f32_16x16x32_bf16 v[6:9], v[146:149], v[230:233], v[6:9]
	v_mfma_f32_16x16x32_bf16 v[2:5], v[178:181], v[230:233], v[2:5]
	v_mfma_f32_16x16x32_bf16 v[54:57], v[160:163], v[210:213], v[54:57]
	v_mfma_f32_16x16x32_bf16 v[46:49], v[182:185], v[210:213], v[46:49]
	v_mfma_f32_16x16x32_bf16 v[38:41], v[160:163], v[218:221], v[38:41]
	v_mfma_f32_16x16x32_bf16 v[30:33], v[182:185], v[218:221], v[30:33]
	v_mfma_f32_16x16x32_bf16 v[22:25], v[160:163], v[226:229], v[22:25]
	v_mfma_f32_16x16x32_bf16 v[14:17], v[182:185], v[226:229], v[14:17]
	v_mfma_f32_16x16x32_bf16 v[6:9], v[160:163], v[234:237], v[6:9]
	v_mfma_f32_16x16x32_bf16 v[2:5], v[182:185], v[234:237], v[2:5]
	s_barrier
	s_setprio 0
	s_add_i32 s84, s84, 2
	s_add_u32 s66, s66, 0x100
	s_addc_u32 s67, s67, 0
	s_add_u32 s82, s82, 0x100
	s_addc_u32 s83, s83, 0
	s_cmp_gt_u32 s84, 29
	s_cbranch_scc0 .LBB0_903
	s_and_b64 vcc, exec, s[10:11]
	s_cbranch_vccz .LBB0_906
	s_barrier

.LBB0_1035:
	s_add_u32 s46, s64, 0xfff80080
	s_addc_u32 s47, s65, -1
	s_add_i32 s48, 0, 0x10000
	s_cmp_eq_u32 s84, 28
	s_cselect_b32 s67, s17, s47
	s_cselect_b32 s66, s80, s46
	v_add_u32_e32 v140, s48, v142
	s_cselect_b32 s61, s13, s83
	s_cselect_b32 s60, s81, s82
	s_add_i32 s49, 0, 0x14000
	ds_read_b128 v[146:149], v140
	ds_read_b128 v[150:153], v140 offset:1024
	ds_read_b128 v[154:157], v140 offset:2048
	ds_read_b128 v[158:161], v140 offset:3072
	v_add_u32_e32 v140, s49, v142
	ds_read_b128 v[162:165], v140
	ds_read_b128 v[178:181], v140 offset:1024
	ds_read_b128 v[182:185], v140 offset:2048
	ds_read_b128 v[186:189], v140 offset:3072
	v_lshl_add_u64 v[140:141], s[64:65], 0, v[136:137]
	s_add_i32 m0, s23, 0xc000
	ds_read_b128 v[206:209], v144
	ds_read_b128 v[210:213], v144 offset:1024
	ds_read_b128 v[214:217], v144 offset:2048
	ds_read_b128 v[218:221], v144 offset:3072
	ds_read_b128 v[222:225], v144 offset:4096
	ds_read_b128 v[226:229], v144 offset:5120
	ds_read_b128 v[230:233], v144 offset:6144
	ds_read_b128 v[234:237], v144 offset:7168
	global_load_lds_dwordx4 v[140:141], off
	v_lshl_add_u64 v[140:141], s[64:65], 0, v[138:139]
	s_add_i32 m0, s23, 0xe000
	s_nop 0
	global_load_lds_dwordx4 v[140:141], off
	s_waitcnt vmcnt(8)
	s_waitcnt lgkmcnt(0)
	s_setprio 1
	s_waitcnt lgkmcnt(0)
	v_mfma_f32_16x16x32_bf16 v[126:129], v[146:149], v[206:209], v[126:129]
	v_mfma_f32_16x16x32_bf16 v[122:125], v[154:157], v[206:209], v[122:125]
	v_mfma_f32_16x16x32_bf16 v[110:113], v[146:149], v[214:217], v[110:113]
	v_mfma_f32_16x16x32_bf16 v[106:109], v[154:157], v[214:217], v[106:109]
	s_barrier
	v_mfma_f32_16x16x32_bf16 v[94:97], v[146:149], v[222:225], v[94:97]
	v_mfma_f32_16x16x32_bf16 v[90:93], v[154:157], v[222:225], v[90:93]
	v_mfma_f32_16x16x32_bf16 v[78:81], v[146:149], v[230:233], v[78:81]
	v_mfma_f32_16x16x32_bf16 v[74:77], v[154:157], v[230:233], v[74:77]
	v_mfma_f32_16x16x32_bf16 v[126:129], v[150:153], v[210:213], v[126:129]
	v_mfma_f32_16x16x32_bf16 v[122:125], v[158:161], v[210:213], v[122:125]
	v_mfma_f32_16x16x32_bf16 v[110:113], v[150:153], v[218:221], v[110:113]
	v_mfma_f32_16x16x32_bf16 v[106:109], v[158:161], v[218:221], v[106:109]
	v_mfma_f32_16x16x32_bf16 v[94:97], v[150:153], v[226:229], v[94:97]
	v_mfma_f32_16x16x32_bf16 v[90:93], v[158:161], v[226:229], v[90:93]
	v_mfma_f32_16x16x32_bf16 v[78:81], v[150:153], v[234:237], v[78:81]
	v_mfma_f32_16x16x32_bf16 v[74:77], v[158:161], v[234:237], v[74:77]
	v_mfma_f32_16x16x32_bf16 v[118:121], v[162:165], v[206:209], v[118:121]
	v_mfma_f32_16x16x32_bf16 v[114:117], v[182:185], v[206:209], v[114:117]
	v_mfma_f32_16x16x32_bf16 v[102:105], v[162:165], v[214:217], v[102:105]
	v_mfma_f32_16x16x32_bf16 v[98:101], v[182:185], v[214:217], v[98:101]
	v_mfma_f32_16x16x32_bf16 v[86:89], v[162:165], v[222:225], v[86:89]
	v_mfma_f32_16x16x32_bf16 v[82:85], v[182:185], v[222:225], v[82:85]
	v_mfma_f32_16x16x32_bf16 v[70:73], v[162:165], v[230:233], v[70:73]
	v_mfma_f32_16x16x32_bf16 v[66:69], v[182:185], v[230:233], v[66:69]
	v_mfma_f32_16x16x32_bf16 v[118:121], v[178:181], v[210:213], v[118:121]
	v_mfma_f32_16x16x32_bf16 v[114:117], v[186:189], v[210:213], v[114:117]
	v_mfma_f32_16x16x32_bf16 v[102:105], v[178:181], v[218:221], v[102:105]
	v_mfma_f32_16x16x32_bf16 v[98:101], v[186:189], v[218:221], v[98:101]
	v_mfma_f32_16x16x32_bf16 v[86:89], v[178:181], v[226:229], v[86:89]
	v_mfma_f32_16x16x32_bf16 v[82:85], v[186:189], v[226:229], v[82:85]
	v_mfma_f32_16x16x32_bf16 v[70:73], v[178:181], v[234:237], v[70:73]
	v_mfma_f32_16x16x32_bf16 v[66:69], v[186:189], v[234:237], v[66:69]
	s_barrier
	s_setprio 0
	s_add_i32 s46, s48, s72
	v_lshl_add_u64 v[140:141], s[60:61], 0, v[166:167]
	s_mov_b32 m0, s46
	ds_read_b128 v[206:209], v144 offset:16384
	ds_read_b128 v[210:213], v144 offset:17408
	ds_read_b128 v[214:217], v144 offset:18432
	ds_read_b128 v[218:221], v144 offset:19456
	ds_read_b128 v[222:225], v144 offset:20480
	ds_read_b128 v[226:229], v144 offset:21504
	ds_read_b128 v[230:233], v144 offset:22528
	ds_read_b128 v[234:237], v144 offset:23552
	global_load_lds_dwordx4 v[140:141], off
	s_add_i32 m0, s46, 0x2000
	s_add_u32 s46, s60, 0x80000
	v_lshl_add_u64 v[242:243], s[60:61], 0, v[134:135]
	s_addc_u32 s47, s61, 0
	s_add_i32 s48, s49, s72
	global_load_lds_dwordx4 v[242:243], off
	v_lshl_add_u64 v[244:245], s[46:47], 0, v[166:167]
	s_mov_b32 m0, s48
	v_lshl_add_u64 v[246:247], s[66:67], 0, v[132:133]
	global_load_lds_dwordx4 v[244:245], off
	v_lshl_add_u64 v[244:245], s[46:47], 0, v[134:135]
	s_add_i32 m0, s48, 0x2000
	s_nop 0
	global_load_lds_dwordx4 v[244:245], off
	v_lshl_add_u64 v[244:245], s[66:67], 0, v[130:131]
	s_mov_b32 m0, s23
	s_nop 0
	global_load_lds_dwordx4 v[244:245], off
	s_mov_b32 m0, s73
	s_nop 0
	global_load_lds_dwordx4 v[246:247], off
	s_waitcnt vmcnt(8)
	s_waitcnt lgkmcnt(0)
	s_setprio 1
	s_waitcnt lgkmcnt(0)
	v_mfma_f32_16x16x32_bf16 v[62:65], v[146:149], v[206:209], v[62:65]
	v_mfma_f32_16x16x32_bf16 v[58:61], v[154:157], v[206:209], v[58:61]
	s_barrier
	v_mfma_f32_16x16x32_bf16 v[46:49], v[146:149], v[214:217], v[46:49]
	v_mfma_f32_16x16x32_bf16 v[42:45], v[154:157], v[214:217], v[42:45]
	v_mfma_f32_16x16x32_bf16 v[30:33], v[146:149], v[222:225], v[30:33]
	v_mfma_f32_16x16x32_bf16 v[26:29], v[154:157], v[222:225], v[26:29]
	v_mfma_f32_16x16x32_bf16 v[14:17], v[146:149], v[230:233], v[14:17]
	v_mfma_f32_16x16x32_bf16 v[10:13], v[154:157], v[230:233], v[10:13]
	v_mfma_f32_16x16x32_bf16 v[62:65], v[150:153], v[210:213], v[62:65]
	v_mfma_f32_16x16x32_bf16 v[58:61], v[158:161], v[210:213], v[58:61]
	v_mfma_f32_16x16x32_bf16 v[46:49], v[150:153], v[218:221], v[46:49]
	v_mfma_f32_16x16x32_bf16 v[42:45], v[158:161], v[218:221], v[42:45]
	v_mfma_f32_16x16x32_bf16 v[30:33], v[150:153], v[226:229], v[30:33]
	v_mfma_f32_16x16x32_bf16 v[26:29], v[158:161], v[226:229], v[26:29]
	v_mfma_f32_16x16x32_bf16 v[14:17], v[150:153], v[234:237], v[14:17]
	v_mfma_f32_16x16x32_bf16 v[10:13], v[158:161], v[234:237], v[10:13]
	v_mfma_f32_16x16x32_bf16 v[54:57], v[162:165], v[206:209], v[54:57]
	v_mfma_f32_16x16x32_bf16 v[50:53], v[182:185], v[206:209], v[50:53]
	v_mfma_f32_16x16x32_bf16 v[38:41], v[162:165], v[214:217], v[38:41]
	v_mfma_f32_16x16x32_bf16 v[34:37], v[182:185], v[214:217], v[34:37]
	v_mfma_f32_16x16x32_bf16 v[22:25], v[162:165], v[222:225], v[22:25]
	v_mfma_f32_16x16x32_bf16 v[18:21], v[182:185], v[222:225], v[18:21]
	v_mfma_f32_16x16x32_bf16 v[6:9], v[162:165], v[230:233], v[6:9]
	v_mfma_f32_16x16x32_bf16 v[2:5], v[182:185], v[230:233], v[2:5]
	v_mfma_f32_16x16x32_bf16 v[54:57], v[178:181], v[210:213], v[54:57]
	v_mfma_f32_16x16x32_bf16 v[50:53], v[186:189], v[210:213], v[50:53]
	v_mfma_f32_16x16x32_bf16 v[38:41], v[178:181], v[218:221], v[38:41]
	v_mfma_f32_16x16x32_bf16 v[34:37], v[186:189], v[218:221], v[34:37]
	v_mfma_f32_16x16x32_bf16 v[22:25], v[178:181], v[226:229], v[22:25]
	v_mfma_f32_16x16x32_bf16 v[18:21], v[186:189], v[226:229], v[18:21]
	v_mfma_f32_16x16x32_bf16 v[6:9], v[178:181], v[234:237], v[6:9]
	v_mfma_f32_16x16x32_bf16 v[2:5], v[186:189], v[234:237], v[2:5]
	s_barrier
	s_setprio 0
	s_add_i32 s48, 0, 0x18000
	v_add_u32_e32 v145, s48, v142
	s_add_i32 s49, 0, 0x1c000
	ds_read_b128 v[146:149], v145
	ds_read_b128 v[150:153], v145 offset:1024
	ds_read_b128 v[154:157], v145 offset:2048
	ds_read_b128 v[158:161], v145 offset:3072
	v_add_u32_e32 v145, s49, v142
	ds_read_b128 v[162:165], v145
	ds_read_b128 v[178:181], v145 offset:1024
	ds_read_b128 v[182:185], v145 offset:2048
	ds_read_b128 v[186:189], v145 offset:3072
	s_add_u32 s46, s66, 0x80000
	s_addc_u32 s47, s67, 0
	s_mov_b32 m0, s74
	v_lshl_add_u64 v[248:249], s[46:47], 0, v[130:131]
	ds_read_b128 v[206:209], v144 offset:32768
	ds_read_b128 v[210:213], v144 offset:33792
	ds_read_b128 v[214:217], v144 offset:34816
	ds_read_b128 v[218:221], v144 offset:35840
	ds_read_b128 v[222:225], v144 offset:36864
	ds_read_b128 v[226:229], v144 offset:37888
	ds_read_b128 v[230:233], v144 offset:38912
	ds_read_b128 v[234:237], v144 offset:39936
	global_load_lds_dwordx4 v[248:249], off
	v_lshl_add_u64 v[248:249], s[46:47], 0, v[132:133]
	s_mov_b32 m0, s75
	s_nop 0
	global_load_lds_dwordx4 v[248:249], off
	s_waitcnt vmcnt(8)
	s_waitcnt lgkmcnt(0)
	s_setprio 1
	s_waitcnt lgkmcnt(0)
	v_mfma_f32_16x16x32_bf16 v[126:129], v[146:149], v[206:209], v[126:129]
	v_mfma_f32_16x16x32_bf16 v[122:125], v[154:157], v[206:209], v[122:125]
	v_mfma_f32_16x16x32_bf16 v[110:113], v[146:149], v[214:217], v[110:113]
	v_mfma_f32_16x16x32_bf16 v[106:109], v[154:157], v[214:217], v[106:109]
	s_barrier
	v_mfma_f32_16x16x32_bf16 v[94:97], v[146:149], v[222:225], v[94:97]
	v_mfma_f32_16x16x32_bf16 v[90:93], v[154:157], v[222:225], v[90:93]
	v_mfma_f32_16x16x32_bf16 v[78:81], v[146:149], v[230:233], v[78:81]
	v_mfma_f32_16x16x32_bf16 v[74:77], v[154:157], v[230:233], v[74:77]
	v_mfma_f32_16x16x32_bf16 v[126:129], v[150:153], v[210:213], v[126:129]
	v_mfma_f32_16x16x32_bf16 v[122:125], v[158:161], v[210:213], v[122:125]
	v_mfma_f32_16x16x32_bf16 v[110:113], v[150:153], v[218:221], v[110:113]
	v_mfma_f32_16x16x32_bf16 v[106:109], v[158:161], v[218:221], v[106:109]
	v_mfma_f32_16x16x32_bf16 v[94:97], v[150:153], v[226:229], v[94:97]
	v_mfma_f32_16x16x32_bf16 v[90:93], v[158:161], v[226:229], v[90:93]
	v_mfma_f32_16x16x32_bf16 v[78:81], v[150:153], v[234:237], v[78:81]
	v_mfma_f32_16x16x32_bf16 v[74:77], v[158:161], v[234:237], v[74:77]
	v_mfma_f32_16x16x32_bf16 v[118:121], v[162:165], v[206:209], v[118:121]
	v_mfma_f32_16x16x32_bf16 v[114:117], v[182:185], v[206:209], v[114:117]
	v_mfma_f32_16x16x32_bf16 v[102:105], v[162:165], v[214:217], v[102:105]
	v_mfma_f32_16x16x32_bf16 v[98:101], v[182:185], v[214:217], v[98:101]
	v_mfma_f32_16x16x32_bf16 v[86:89], v[162:165], v[222:225], v[86:89]
	v_mfma_f32_16x16x32_bf16 v[82:85], v[182:185], v[222:225], v[82:85]
	v_mfma_f32_16x16x32_bf16 v[70:73], v[162:165], v[230:233], v[70:73]
	v_mfma_f32_16x16x32_bf16 v[66:69], v[182:185], v[230:233], v[66:69]
	v_mfma_f32_16x16x32_bf16 v[118:121], v[178:181], v[210:213], v[118:121]
	v_mfma_f32_16x16x32_bf16 v[114:117], v[186:189], v[210:213], v[114:117]
	v_mfma_f32_16x16x32_bf16 v[102:105], v[178:181], v[218:221], v[102:105]
	v_mfma_f32_16x16x32_bf16 v[98:101], v[186:189], v[218:221], v[98:101]
	v_mfma_f32_16x16x32_bf16 v[86:89], v[178:181], v[226:229], v[86:89]
	v_mfma_f32_16x16x32_bf16 v[82:85], v[186:189], v[226:229], v[82:85]
	v_mfma_f32_16x16x32_bf16 v[70:73], v[178:181], v[234:237], v[70:73]
	v_mfma_f32_16x16x32_bf16 v[66:69], v[186:189], v[234:237], v[66:69]
	s_barrier
	s_setprio 0
	s_add_i32 s46, s48, s72
	v_lshl_add_u64 v[140:141], v[140:141], 0, s[42:43]
	s_mov_b32 m0, s46
	ds_read_b128 v[206:209], v144 offset:49152
	ds_read_b128 v[210:213], v144 offset:50176
	ds_read_b128 v[214:217], v144 offset:51200
	ds_read_b128 v[218:221], v144 offset:52224
	ds_read_b128 v[222:225], v144 offset:53248
	ds_read_b128 v[226:229], v144 offset:54272
	ds_read_b128 v[230:233], v144 offset:55296
	ds_read_b128 v[234:237], v144 offset:56320
	global_load_lds_dwordx4 v[140:141], off
	s_add_i32 m0, s46, 0x2000
	s_add_u32 s46, s60, 0x80080
	v_lshl_add_u64 v[140:141], v[242:243], 0, s[42:43]
	s_addc_u32 s47, s61, 0
	s_add_i32 s48, s49, s72
	global_load_lds_dwordx4 v[140:141], off
	v_lshl_add_u64 v[140:141], s[46:47], 0, v[166:167]
	s_mov_b32 m0, s48
	s_nop 0
	global_load_lds_dwordx4 v[140:141], off
	v_lshl_add_u64 v[140:141], s[46:47], 0, v[134:135]
	s_add_i32 m0, s48, 0x2000
	s_nop 0
	global_load_lds_dwordx4 v[140:141], off
	v_lshl_add_u64 v[140:141], v[244:245], 0, s[42:43]
	s_mov_b32 m0, s76
	s_nop 0
	global_load_lds_dwordx4 v[140:141], off
	v_lshl_add_u64 v[140:141], v[246:247], 0, s[42:43]
	s_mov_b32 m0, s77
	s_nop 0
	global_load_lds_dwordx4 v[140:141], off
	s_waitcnt vmcnt(8)
	s_waitcnt lgkmcnt(0)
	s_setprio 1
	s_waitcnt lgkmcnt(0)
	v_mfma_f32_16x16x32_bf16 v[62:65], v[146:149], v[206:209], v[62:65]
	v_mfma_f32_16x16x32_bf16 v[58:61], v[154:157], v[206:209], v[58:61]
	s_barrier
	v_mfma_f32_16x16x32_bf16 v[46:49], v[146:149], v[214:217], v[46:49]
	v_mfma_f32_16x16x32_bf16 v[42:45], v[154:157], v[214:217], v[42:45]
	v_mfma_f32_16x16x32_bf16 v[30:33], v[146:149], v[222:225], v[30:33]
	v_mfma_f32_16x16x32_bf16 v[26:29], v[154:157], v[222:225], v[26:29]
	v_mfma_f32_16x16x32_bf16 v[14:17], v[146:149], v[230:233], v[14:17]
	v_mfma_f32_16x16x32_bf16 v[10:13], v[154:157], v[230:233], v[10:13]
	v_mfma_f32_16x16x32_bf16 v[62:65], v[150:153], v[210:213], v[62:65]
	v_mfma_f32_16x16x32_bf16 v[58:61], v[158:161], v[210:213], v[58:61]
	v_mfma_f32_16x16x32_bf16 v[46:49], v[150:153], v[218:221], v[46:49]
	v_mfma_f32_16x16x32_bf16 v[42:45], v[158:161], v[218:221], v[42:45]
	v_mfma_f32_16x16x32_bf16 v[30:33], v[150:153], v[226:229], v[30:33]
	v_mfma_f32_16x16x32_bf16 v[26:29], v[158:161], v[226:229], v[26:29]
	v_mfma_f32_16x16x32_bf16 v[14:17], v[150:153], v[234:237], v[14:17]
	v_mfma_f32_16x16x32_bf16 v[10:13], v[158:161], v[234:237], v[10:13]
	v_mfma_f32_16x16x32_bf16 v[54:57], v[162:165], v[206:209], v[54:57]
	v_mfma_f32_16x16x32_bf16 v[50:53], v[182:185], v[206:209], v[50:53]
	v_mfma_f32_16x16x32_bf16 v[38:41], v[162:165], v[214:217], v[38:41]
	v_mfma_f32_16x16x32_bf16 v[34:37], v[182:185], v[214:217], v[34:37]
	v_mfma_f32_16x16x32_bf16 v[22:25], v[162:165], v[222:225], v[22:25]
	v_mfma_f32_16x16x32_bf16 v[18:21], v[182:185], v[222:225], v[18:21]
	v_mfma_f32_16x16x32_bf16 v[6:9], v[162:165], v[230:233], v[6:9]
	v_mfma_f32_16x16x32_bf16 v[2:5], v[182:185], v[230:233], v[2:5]
	v_mfma_f32_16x16x32_bf16 v[54:57], v[178:181], v[210:213], v[54:57]
	v_mfma_f32_16x16x32_bf16 v[50:53], v[186:189], v[210:213], v[50:53]
	v_mfma_f32_16x16x32_bf16 v[38:41], v[178:181], v[218:221], v[38:41]
	v_mfma_f32_16x16x32_bf16 v[34:37], v[186:189], v[218:221], v[34:37]
	v_mfma_f32_16x16x32_bf16 v[22:25], v[178:181], v[226:229], v[22:25]
	v_mfma_f32_16x16x32_bf16 v[18:21], v[186:189], v[226:229], v[18:21]
	v_mfma_f32_16x16x32_bf16 v[6:9], v[178:181], v[234:237], v[6:9]
	v_mfma_f32_16x16x32_bf16 v[2:5], v[186:189], v[234:237], v[2:5]
	s_barrier
	s_setprio 0
	s_add_i32 s84, s84, 2
	s_add_u32 s64, s64, 0x100
	s_addc_u32 s65, s65, 0
	s_add_u32 s82, s82, 0x100
	s_addc_u32 s83, s83, 0
	s_cmp_gt_u32 s84, 29
	s_cbranch_scc0 .LBB0_1035
	s_and_b64 vcc, exec, s[10:11]
	s_cbranch_vccz .LBB0_1038
	s_barrier

.LBB0_1112:
	s_add_u32 s46, s64, 0xffe00080
	s_addc_u32 s47, s65, -1
	s_add_i32 s48, 0, 0x10000
	s_cmpk_eq_i32 s84, 0x7c
	s_cselect_b32 s67, s19, s47
	s_cselect_b32 s66, s80, s46
	s_cselect_b32 s61, s17, s83
	s_cselect_b32 s60, s81, s82
	s_add_i32 s49, 0, 0x14000
	v_add_u32_e32 v142, s48, v182
	v_add_u32_e32 v164, s49, v182
	ds_read_b128 v[130:133], v142
	ds_read_b128 v[134:137], v142 offset:1024
	ds_read_b128 v[138:141], v142 offset:2048
	ds_read_b128 v[142:145], v142 offset:3072
	ds_read_b128 v[146:149], v164
	ds_read_b128 v[160:163], v164 offset:1024
	ds_read_b128 v[178:181], v164 offset:2048
	ds_read_b128 v[186:189], v164 offset:3072
	v_lshl_add_u64 v[164:165], s[64:65], 0, v[156:157]
	s_add_i32 m0, s63, 0xc000
	ds_read_b128 v[206:209], v184
	ds_read_b128 v[210:213], v184 offset:1024
	ds_read_b128 v[214:217], v184 offset:2048
	ds_read_b128 v[218:221], v184 offset:3072
	ds_read_b128 v[222:225], v184 offset:4096
	ds_read_b128 v[226:229], v184 offset:5120
	ds_read_b128 v[230:233], v184 offset:6144
	ds_read_b128 v[234:237], v184 offset:7168
	global_load_lds_dwordx4 v[164:165], off
	v_lshl_add_u64 v[164:165], s[64:65], 0, v[158:159]
	s_add_i32 m0, s63, 0xe000
	s_nop 0
	global_load_lds_dwordx4 v[164:165], off
	s_waitcnt vmcnt(8)
	s_waitcnt lgkmcnt(0)
	s_setprio 1
	s_waitcnt lgkmcnt(0)
	v_mfma_f32_16x16x32_bf16 v[126:129], v[130:133], v[206:209], v[126:129]
	v_mfma_f32_16x16x32_bf16 v[122:125], v[138:141], v[206:209], v[122:125]
	v_mfma_f32_16x16x32_bf16 v[118:121], v[130:133], v[214:217], v[118:121]
	v_mfma_f32_16x16x32_bf16 v[114:117], v[138:141], v[214:217], v[114:117]
	s_barrier
	v_mfma_f32_16x16x32_bf16 v[94:97], v[130:133], v[222:225], v[94:97]
	v_mfma_f32_16x16x32_bf16 v[90:93], v[138:141], v[222:225], v[90:93]
	v_mfma_f32_16x16x32_bf16 v[82:85], v[130:133], v[230:233], v[82:85]
	v_mfma_f32_16x16x32_bf16 v[74:77], v[138:141], v[230:233], v[74:77]
	v_mfma_f32_16x16x32_bf16 v[126:129], v[134:137], v[210:213], v[126:129]
	v_mfma_f32_16x16x32_bf16 v[122:125], v[142:145], v[210:213], v[122:125]
	v_mfma_f32_16x16x32_bf16 v[118:121], v[134:137], v[218:221], v[118:121]
	v_mfma_f32_16x16x32_bf16 v[114:117], v[142:145], v[218:221], v[114:117]
	v_mfma_f32_16x16x32_bf16 v[94:97], v[134:137], v[226:229], v[94:97]
	v_mfma_f32_16x16x32_bf16 v[90:93], v[142:145], v[226:229], v[90:93]
	v_mfma_f32_16x16x32_bf16 v[82:85], v[134:137], v[234:237], v[82:85]
	v_mfma_f32_16x16x32_bf16 v[74:77], v[142:145], v[234:237], v[74:77]
	v_mfma_f32_16x16x32_bf16 v[110:113], v[146:149], v[206:209], v[110:113]
	v_mfma_f32_16x16x32_bf16 v[106:109], v[178:181], v[206:209], v[106:109]
	v_mfma_f32_16x16x32_bf16 v[102:105], v[146:149], v[214:217], v[102:105]
	v_mfma_f32_16x16x32_bf16 v[98:101], v[178:181], v[214:217], v[98:101]
	v_mfma_f32_16x16x32_bf16 v[86:89], v[146:149], v[222:225], v[86:89]
	v_mfma_f32_16x16x32_bf16 v[78:81], v[178:181], v[222:225], v[78:81]
	v_mfma_f32_16x16x32_bf16 v[70:73], v[146:149], v[230:233], v[70:73]
	v_mfma_f32_16x16x32_bf16 v[66:69], v[178:181], v[230:233], v[66:69]
	v_mfma_f32_16x16x32_bf16 v[110:113], v[160:163], v[210:213], v[110:113]
	v_mfma_f32_16x16x32_bf16 v[106:109], v[186:189], v[210:213], v[106:109]
	v_mfma_f32_16x16x32_bf16 v[102:105], v[160:163], v[218:221], v[102:105]
	v_mfma_f32_16x16x32_bf16 v[98:101], v[186:189], v[218:221], v[98:101]
	v_mfma_f32_16x16x32_bf16 v[86:89], v[160:163], v[226:229], v[86:89]
	v_mfma_f32_16x16x32_bf16 v[78:81], v[186:189], v[226:229], v[78:81]
	v_mfma_f32_16x16x32_bf16 v[70:73], v[160:163], v[234:237], v[70:73]
	v_mfma_f32_16x16x32_bf16 v[66:69], v[186:189], v[234:237], v[66:69]
	s_barrier
	s_setprio 0
	s_add_i32 s46, s48, s72
	v_lshl_add_u64 v[164:165], s[60:61], 0, v[166:167]
	s_mov_b32 m0, s46
	ds_read_b128 v[206:209], v184 offset:16384
	ds_read_b128 v[210:213], v184 offset:17408
	ds_read_b128 v[214:217], v184 offset:18432
	ds_read_b128 v[218:221], v184 offset:19456
	ds_read_b128 v[222:225], v184 offset:20480
	ds_read_b128 v[226:229], v184 offset:21504
	ds_read_b128 v[230:233], v184 offset:22528
	ds_read_b128 v[234:237], v184 offset:23552
	global_load_lds_dwordx4 v[164:165], off
	s_add_i32 m0, s46, 0x2000
	s_add_u32 s46, s60, 0x200000
	v_lshl_add_u64 v[242:243], s[60:61], 0, v[154:155]
	s_addc_u32 s47, s61, 0
	s_add_i32 s48, s49, s72
	global_load_lds_dwordx4 v[242:243], off
	v_lshl_add_u64 v[244:245], s[46:47], 0, v[166:167]
	s_mov_b32 m0, s48
	v_lshl_add_u64 v[246:247], s[66:67], 0, v[152:153]
	global_load_lds_dwordx4 v[244:245], off
	v_lshl_add_u64 v[244:245], s[46:47], 0, v[154:155]
	s_add_i32 m0, s48, 0x2000
	s_nop 0
	global_load_lds_dwordx4 v[244:245], off
	v_lshl_add_u64 v[244:245], s[66:67], 0, v[150:151]
	s_mov_b32 m0, s63
	s_nop 0
	global_load_lds_dwordx4 v[244:245], off
	s_mov_b32 m0, s73
	s_nop 0
	global_load_lds_dwordx4 v[246:247], off
	s_waitcnt vmcnt(8)
	s_waitcnt lgkmcnt(0)
	s_setprio 1
	s_waitcnt lgkmcnt(0)
	v_mfma_f32_16x16x32_bf16 v[62:65], v[130:133], v[206:209], v[62:65]
	v_mfma_f32_16x16x32_bf16 v[58:61], v[138:141], v[206:209], v[58:61]
	s_barrier
	v_mfma_f32_16x16x32_bf16 v[50:53], v[130:133], v[214:217], v[50:53]
	v_mfma_f32_16x16x32_bf16 v[42:45], v[138:141], v[214:217], v[42:45]
	v_mfma_f32_16x16x32_bf16 v[34:37], v[130:133], v[222:225], v[34:37]
	v_mfma_f32_16x16x32_bf16 v[26:29], v[138:141], v[222:225], v[26:29]
	v_mfma_f32_16x16x32_bf16 v[18:21], v[130:133], v[230:233], v[18:21]
	v_mfma_f32_16x16x32_bf16 v[10:13], v[138:141], v[230:233], v[10:13]
	v_mfma_f32_16x16x32_bf16 v[62:65], v[134:137], v[210:213], v[62:65]
	v_mfma_f32_16x16x32_bf16 v[58:61], v[142:145], v[210:213], v[58:61]
	v_mfma_f32_16x16x32_bf16 v[50:53], v[134:137], v[218:221], v[50:53]
	v_mfma_f32_16x16x32_bf16 v[42:45], v[142:145], v[218:221], v[42:45]
	v_mfma_f32_16x16x32_bf16 v[34:37], v[134:137], v[226:229], v[34:37]
	v_mfma_f32_16x16x32_bf16 v[26:29], v[142:145], v[226:229], v[26:29]
	v_mfma_f32_16x16x32_bf16 v[18:21], v[134:137], v[234:237], v[18:21]
	v_mfma_f32_16x16x32_bf16 v[10:13], v[142:145], v[234:237], v[10:13]
	v_mfma_f32_16x16x32_bf16 v[54:57], v[146:149], v[206:209], v[54:57]
	v_mfma_f32_16x16x32_bf16 v[46:49], v[178:181], v[206:209], v[46:49]
	v_mfma_f32_16x16x32_bf16 v[38:41], v[146:149], v[214:217], v[38:41]
	v_mfma_f32_16x16x32_bf16 v[30:33], v[178:181], v[214:217], v[30:33]
	v_mfma_f32_16x16x32_bf16 v[22:25], v[146:149], v[222:225], v[22:25]
	v_mfma_f32_16x16x32_bf16 v[14:17], v[178:181], v[222:225], v[14:17]
	v_mfma_f32_16x16x32_bf16 v[6:9], v[146:149], v[230:233], v[6:9]
	v_mfma_f32_16x16x32_bf16 v[2:5], v[178:181], v[230:233], v[2:5]
	v_mfma_f32_16x16x32_bf16 v[54:57], v[160:163], v[210:213], v[54:57]
	v_mfma_f32_16x16x32_bf16 v[46:49], v[186:189], v[210:213], v[46:49]
	v_mfma_f32_16x16x32_bf16 v[38:41], v[160:163], v[218:221], v[38:41]
	v_mfma_f32_16x16x32_bf16 v[30:33], v[186:189], v[218:221], v[30:33]
	v_mfma_f32_16x16x32_bf16 v[22:25], v[160:163], v[226:229], v[22:25]
	v_mfma_f32_16x16x32_bf16 v[14:17], v[186:189], v[226:229], v[14:17]
	v_mfma_f32_16x16x32_bf16 v[6:9], v[160:163], v[234:237], v[6:9]
	v_mfma_f32_16x16x32_bf16 v[2:5], v[186:189], v[234:237], v[2:5]
	s_barrier
	s_setprio 0
	s_add_i32 s48, 0, 0x18000
	s_add_i32 s49, 0, 0x1c000
	v_add_u32_e32 v142, s48, v182
	v_add_u32_e32 v185, s49, v182
	ds_read_b128 v[130:133], v142
	ds_read_b128 v[134:137], v142 offset:1024
	ds_read_b128 v[138:141], v142 offset:2048
	ds_read_b128 v[142:145], v142 offset:3072
	ds_read_b128 v[146:149], v185
	ds_read_b128 v[160:163], v185 offset:1024
	ds_read_b128 v[178:181], v185 offset:2048
	ds_read_b128 v[186:189], v185 offset:3072
	s_add_u32 s46, s66, 0x200000
	s_addc_u32 s47, s67, 0
	s_mov_b32 m0, s74
	v_lshl_add_u64 v[248:249], s[46:47], 0, v[150:151]
	ds_read_b128 v[206:209], v184 offset:32768
	ds_read_b128 v[210:213], v184 offset:33792
	ds_read_b128 v[214:217], v184 offset:34816
	ds_read_b128 v[218:221], v184 offset:35840
	ds_read_b128 v[222:225], v184 offset:36864
	ds_read_b128 v[226:229], v184 offset:37888
	ds_read_b128 v[230:233], v184 offset:38912
	ds_read_b128 v[234:237], v184 offset:39936
	global_load_lds_dwordx4 v[248:249], off
	v_lshl_add_u64 v[248:249], s[46:47], 0, v[152:153]
	s_mov_b32 m0, s75
	s_nop 0
	global_load_lds_dwordx4 v[248:249], off
	s_waitcnt vmcnt(8)
	s_waitcnt lgkmcnt(0)
	s_setprio 1
	s_waitcnt lgkmcnt(0)
	v_mfma_f32_16x16x32_bf16 v[126:129], v[130:133], v[206:209], v[126:129]
	v_mfma_f32_16x16x32_bf16 v[122:125], v[138:141], v[206:209], v[122:125]
	v_mfma_f32_16x16x32_bf16 v[118:121], v[130:133], v[214:217], v[118:121]
	v_mfma_f32_16x16x32_bf16 v[114:117], v[138:141], v[214:217], v[114:117]
	s_barrier
	v_mfma_f32_16x16x32_bf16 v[94:97], v[130:133], v[222:225], v[94:97]
	v_mfma_f32_16x16x32_bf16 v[90:93], v[138:141], v[222:225], v[90:93]
	v_mfma_f32_16x16x32_bf16 v[82:85], v[130:133], v[230:233], v[82:85]
	v_mfma_f32_16x16x32_bf16 v[74:77], v[138:141], v[230:233], v[74:77]
	v_mfma_f32_16x16x32_bf16 v[126:129], v[134:137], v[210:213], v[126:129]
	v_mfma_f32_16x16x32_bf16 v[122:125], v[142:145], v[210:213], v[122:125]
	v_mfma_f32_16x16x32_bf16 v[118:121], v[134:137], v[218:221], v[118:121]
	v_mfma_f32_16x16x32_bf16 v[114:117], v[142:145], v[218:221], v[114:117]
	v_mfma_f32_16x16x32_bf16 v[94:97], v[134:137], v[226:229], v[94:97]
	v_mfma_f32_16x16x32_bf16 v[90:93], v[142:145], v[226:229], v[90:93]
	v_mfma_f32_16x16x32_bf16 v[82:85], v[134:137], v[234:237], v[82:85]
	v_mfma_f32_16x16x32_bf16 v[74:77], v[142:145], v[234:237], v[74:77]
	v_mfma_f32_16x16x32_bf16 v[110:113], v[146:149], v[206:209], v[110:113]
	v_mfma_f32_16x16x32_bf16 v[106:109], v[178:181], v[206:209], v[106:109]
	v_mfma_f32_16x16x32_bf16 v[102:105], v[146:149], v[214:217], v[102:105]
	v_mfma_f32_16x16x32_bf16 v[98:101], v[178:181], v[214:217], v[98:101]
	v_mfma_f32_16x16x32_bf16 v[86:89], v[146:149], v[222:225], v[86:89]
	v_mfma_f32_16x16x32_bf16 v[78:81], v[178:181], v[222:225], v[78:81]
	v_mfma_f32_16x16x32_bf16 v[70:73], v[146:149], v[230:233], v[70:73]
	v_mfma_f32_16x16x32_bf16 v[66:69], v[178:181], v[230:233], v[66:69]
	v_mfma_f32_16x16x32_bf16 v[110:113], v[160:163], v[210:213], v[110:113]
	v_mfma_f32_16x16x32_bf16 v[106:109], v[186:189], v[210:213], v[106:109]
	v_mfma_f32_16x16x32_bf16 v[102:105], v[160:163], v[218:221], v[102:105]
	v_mfma_f32_16x16x32_bf16 v[98:101], v[186:189], v[218:221], v[98:101]
	v_mfma_f32_16x16x32_bf16 v[86:89], v[160:163], v[226:229], v[86:89]
	v_mfma_f32_16x16x32_bf16 v[78:81], v[186:189], v[226:229], v[78:81]
	v_mfma_f32_16x16x32_bf16 v[70:73], v[160:163], v[234:237], v[70:73]
	v_mfma_f32_16x16x32_bf16 v[66:69], v[186:189], v[234:237], v[66:69]
	s_barrier
	s_setprio 0
	s_add_i32 s46, s48, s72
	v_lshl_add_u64 v[164:165], v[164:165], 0, s[42:43]
	s_mov_b32 m0, s46
	ds_read_b128 v[206:209], v184 offset:49152
	ds_read_b128 v[210:213], v184 offset:50176
	ds_read_b128 v[214:217], v184 offset:51200
	ds_read_b128 v[218:221], v184 offset:52224
	ds_read_b128 v[222:225], v184 offset:53248
	ds_read_b128 v[226:229], v184 offset:54272
	ds_read_b128 v[230:233], v184 offset:55296
	ds_read_b128 v[234:237], v184 offset:56320
	global_load_lds_dwordx4 v[164:165], off
	s_add_i32 m0, s46, 0x2000
	s_add_u32 s46, s60, 0x200080
	v_lshl_add_u64 v[164:165], v[242:243], 0, s[42:43]
	s_addc_u32 s47, s61, 0
	s_add_i32 s48, s49, s72
	global_load_lds_dwordx4 v[164:165], off
	v_lshl_add_u64 v[164:165], s[46:47], 0, v[166:167]
	s_mov_b32 m0, s48
	s_nop 0
	global_load_lds_dwordx4 v[164:165], off
	v_lshl_add_u64 v[164:165], s[46:47], 0, v[154:155]
	s_add_i32 m0, s48, 0x2000
	s_nop 0
	global_load_lds_dwordx4 v[164:165], off
	v_lshl_add_u64 v[164:165], v[244:245], 0, s[42:43]
	s_mov_b32 m0, s76
	s_nop 0
	global_load_lds_dwordx4 v[164:165], off
	v_lshl_add_u64 v[164:165], v[246:247], 0, s[42:43]
	s_mov_b32 m0, s77
	s_nop 0
	global_load_lds_dwordx4 v[164:165], off
	s_waitcnt vmcnt(8)
	s_waitcnt lgkmcnt(0)
	s_setprio 1
	s_waitcnt lgkmcnt(0)
	v_mfma_f32_16x16x32_bf16 v[62:65], v[130:133], v[206:209], v[62:65]
	v_mfma_f32_16x16x32_bf16 v[58:61], v[138:141], v[206:209], v[58:61]
	s_barrier
	v_mfma_f32_16x16x32_bf16 v[50:53], v[130:133], v[214:217], v[50:53]
	v_mfma_f32_16x16x32_bf16 v[42:45], v[138:141], v[214:217], v[42:45]
	v_mfma_f32_16x16x32_bf16 v[34:37], v[130:133], v[222:225], v[34:37]
	v_mfma_f32_16x16x32_bf16 v[26:29], v[138:141], v[222:225], v[26:29]
	v_mfma_f32_16x16x32_bf16 v[18:21], v[130:133], v[230:233], v[18:21]
	v_mfma_f32_16x16x32_bf16 v[10:13], v[138:141], v[230:233], v[10:13]
	v_mfma_f32_16x16x32_bf16 v[62:65], v[134:137], v[210:213], v[62:65]
	v_mfma_f32_16x16x32_bf16 v[58:61], v[142:145], v[210:213], v[58:61]
	v_mfma_f32_16x16x32_bf16 v[50:53], v[134:137], v[218:221], v[50:53]
	v_mfma_f32_16x16x32_bf16 v[42:45], v[142:145], v[218:221], v[42:45]
	v_mfma_f32_16x16x32_bf16 v[34:37], v[134:137], v[226:229], v[34:37]
	v_mfma_f32_16x16x32_bf16 v[26:29], v[142:145], v[226:229], v[26:29]
	v_mfma_f32_16x16x32_bf16 v[18:21], v[134:137], v[234:237], v[18:21]
	v_mfma_f32_16x16x32_bf16 v[10:13], v[142:145], v[234:237], v[10:13]
	v_mfma_f32_16x16x32_bf16 v[54:57], v[146:149], v[206:209], v[54:57]
	v_mfma_f32_16x16x32_bf16 v[46:49], v[178:181], v[206:209], v[46:49]
	v_mfma_f32_16x16x32_bf16 v[38:41], v[146:149], v[214:217], v[38:41]
	v_mfma_f32_16x16x32_bf16 v[30:33], v[178:181], v[214:217], v[30:33]
	v_mfma_f32_16x16x32_bf16 v[22:25], v[146:149], v[222:225], v[22:25]
	v_mfma_f32_16x16x32_bf16 v[14:17], v[178:181], v[222:225], v[14:17]
	v_mfma_f32_16x16x32_bf16 v[6:9], v[146:149], v[230:233], v[6:9]
	v_mfma_f32_16x16x32_bf16 v[2:5], v[178:181], v[230:233], v[2:5]
	v_mfma_f32_16x16x32_bf16 v[54:57], v[160:163], v[210:213], v[54:57]
	v_mfma_f32_16x16x32_bf16 v[46:49], v[186:189], v[210:213], v[46:49]
	v_mfma_f32_16x16x32_bf16 v[38:41], v[160:163], v[218:221], v[38:41]
	v_mfma_f32_16x16x32_bf16 v[30:33], v[186:189], v[218:221], v[30:33]
	v_mfma_f32_16x16x32_bf16 v[22:25], v[160:163], v[226:229], v[22:25]
	v_mfma_f32_16x16x32_bf16 v[14:17], v[186:189], v[226:229], v[14:17]
	v_mfma_f32_16x16x32_bf16 v[6:9], v[160:163], v[234:237], v[6:9]
	v_mfma_f32_16x16x32_bf16 v[2:5], v[186:189], v[234:237], v[2:5]
	s_barrier
	s_setprio 0
	s_add_i32 s84, s84, 2
	s_add_u32 s64, s64, 0x100
	s_addc_u32 s65, s65, 0
	s_add_u32 s82, s82, 0x100
	s_addc_u32 s83, s83, 0
	s_cmpk_gt_u32 s84, 0x7d
	s_cbranch_scc0 .LBB0_1112
	s_and_b64 vcc, exec, s[12:13]
	s_cbranch_vccz .LBB0_1115
	s_barrier

.LBB0_1138:
	s_add_u32 s46, s62, 0xffe00080
	s_addc_u32 s47, s63, -1
	s_add_i32 s48, 0, 0x10000
	s_cmpk_eq_i32 s82, 0x7c
	s_cselect_b32 s65, s17, s47
	s_cselect_b32 s64, s78, s46
	s_cselect_b32 s61, s13, s81
	s_cselect_b32 s60, s79, s80
	s_add_i32 s49, 0, 0x14000
	v_add_u32_e32 v142, s48, v186
	v_add_u32_e32 v164, s49, v186
	ds_read_b128 v[130:133], v142
	ds_read_b128 v[134:137], v142 offset:1024
	ds_read_b128 v[138:141], v142 offset:2048
	ds_read_b128 v[142:145], v142 offset:3072
	ds_read_b128 v[146:149], v164
	ds_read_b128 v[160:163], v164 offset:1024
	ds_read_b128 v[178:181], v164 offset:2048
	ds_read_b128 v[182:185], v164 offset:3072
	v_lshl_add_u64 v[164:165], s[62:63], 0, v[156:157]
	s_add_i32 m0, s71, 0xc000
	ds_read_b128 v[206:209], v188
	ds_read_b128 v[210:213], v188 offset:1024
	ds_read_b128 v[214:217], v188 offset:2048
	ds_read_b128 v[218:221], v188 offset:3072
	ds_read_b128 v[222:225], v188 offset:4096
	ds_read_b128 v[226:229], v188 offset:5120
	ds_read_b128 v[230:233], v188 offset:6144
	ds_read_b128 v[234:237], v188 offset:7168
	global_load_lds_dwordx4 v[164:165], off
	v_lshl_add_u64 v[164:165], s[62:63], 0, v[158:159]
	s_add_i32 m0, s71, 0xe000
	s_nop 0
	global_load_lds_dwordx4 v[164:165], off
	s_waitcnt vmcnt(8)
	s_waitcnt lgkmcnt(0)
	s_setprio 1
	s_waitcnt lgkmcnt(0)
	v_mfma_f32_16x16x32_bf16 v[126:129], v[130:133], v[206:209], v[126:129]
	v_mfma_f32_16x16x32_bf16 v[122:125], v[138:141], v[206:209], v[122:125]
	v_mfma_f32_16x16x32_bf16 v[118:121], v[130:133], v[214:217], v[118:121]
	v_mfma_f32_16x16x32_bf16 v[110:113], v[138:141], v[214:217], v[110:113]
	s_barrier
	v_mfma_f32_16x16x32_bf16 v[94:97], v[130:133], v[222:225], v[94:97]
	v_mfma_f32_16x16x32_bf16 v[90:93], v[138:141], v[222:225], v[90:93]
	v_mfma_f32_16x16x32_bf16 v[82:85], v[130:133], v[230:233], v[82:85]
	v_mfma_f32_16x16x32_bf16 v[74:77], v[138:141], v[230:233], v[74:77]
	v_mfma_f32_16x16x32_bf16 v[126:129], v[134:137], v[210:213], v[126:129]
	v_mfma_f32_16x16x32_bf16 v[122:125], v[142:145], v[210:213], v[122:125]
	v_mfma_f32_16x16x32_bf16 v[118:121], v[134:137], v[218:221], v[118:121]
	v_mfma_f32_16x16x32_bf16 v[110:113], v[142:145], v[218:221], v[110:113]
	v_mfma_f32_16x16x32_bf16 v[94:97], v[134:137], v[226:229], v[94:97]
	v_mfma_f32_16x16x32_bf16 v[90:93], v[142:145], v[226:229], v[90:93]
	v_mfma_f32_16x16x32_bf16 v[82:85], v[134:137], v[234:237], v[82:85]
	v_mfma_f32_16x16x32_bf16 v[74:77], v[142:145], v[234:237], v[74:77]
	v_mfma_f32_16x16x32_bf16 v[114:117], v[146:149], v[206:209], v[114:117]
	v_mfma_f32_16x16x32_bf16 v[106:109], v[178:181], v[206:209], v[106:109]
	v_mfma_f32_16x16x32_bf16 v[102:105], v[146:149], v[214:217], v[102:105]
	v_mfma_f32_16x16x32_bf16 v[98:101], v[178:181], v[214:217], v[98:101]
	v_mfma_f32_16x16x32_bf16 v[86:89], v[146:149], v[222:225], v[86:89]
	v_mfma_f32_16x16x32_bf16 v[78:81], v[178:181], v[222:225], v[78:81]
	v_mfma_f32_16x16x32_bf16 v[70:73], v[146:149], v[230:233], v[70:73]
	v_mfma_f32_16x16x32_bf16 v[66:69], v[178:181], v[230:233], v[66:69]
	v_mfma_f32_16x16x32_bf16 v[114:117], v[160:163], v[210:213], v[114:117]
	v_mfma_f32_16x16x32_bf16 v[106:109], v[182:185], v[210:213], v[106:109]
	v_mfma_f32_16x16x32_bf16 v[102:105], v[160:163], v[218:221], v[102:105]
	v_mfma_f32_16x16x32_bf16 v[98:101], v[182:185], v[218:221], v[98:101]
	v_mfma_f32_16x16x32_bf16 v[86:89], v[160:163], v[226:229], v[86:89]
	v_mfma_f32_16x16x32_bf16 v[78:81], v[182:185], v[226:229], v[78:81]
	v_mfma_f32_16x16x32_bf16 v[70:73], v[160:163], v[234:237], v[70:73]
	v_mfma_f32_16x16x32_bf16 v[66:69], v[182:185], v[234:237], v[66:69]
	s_barrier
	s_setprio 0
	s_add_i32 s46, s48, s70
	v_lshl_add_u64 v[164:165], s[60:61], 0, v[166:167]
	s_mov_b32 m0, s46
	ds_read_b128 v[206:209], v188 offset:16384
	ds_read_b128 v[210:213], v188 offset:17408
	ds_read_b128 v[214:217], v188 offset:18432
	ds_read_b128 v[218:221], v188 offset:19456
	ds_read_b128 v[222:225], v188 offset:20480
	ds_read_b128 v[226:229], v188 offset:21504
	ds_read_b128 v[230:233], v188 offset:22528
	ds_read_b128 v[234:237], v188 offset:23552
	global_load_lds_dwordx4 v[164:165], off
	s_add_i32 m0, s46, 0x2000
	s_add_u32 s46, s60, 0x200000
	v_lshl_add_u64 v[242:243], s[60:61], 0, v[154:155]
	s_addc_u32 s47, s61, 0
	s_add_i32 s48, s49, s70
	global_load_lds_dwordx4 v[242:243], off
	v_lshl_add_u64 v[244:245], s[46:47], 0, v[166:167]
	s_mov_b32 m0, s48
	v_lshl_add_u64 v[246:247], s[64:65], 0, v[152:153]
	global_load_lds_dwordx4 v[244:245], off
	v_lshl_add_u64 v[244:245], s[46:47], 0, v[154:155]
	s_add_i32 m0, s48, 0x2000
	s_nop 0
	global_load_lds_dwordx4 v[244:245], off
	v_lshl_add_u64 v[244:245], s[64:65], 0, v[150:151]
	s_mov_b32 m0, s71
	s_nop 0
	global_load_lds_dwordx4 v[244:245], off
	s_mov_b32 m0, s72
	s_nop 0
	global_load_lds_dwordx4 v[246:247], off
	s_waitcnt vmcnt(8)
	s_waitcnt lgkmcnt(0)
	s_setprio 1
	s_waitcnt lgkmcnt(0)
	v_mfma_f32_16x16x32_bf16 v[62:65], v[130:133], v[206:209], v[62:65]
	v_mfma_f32_16x16x32_bf16 v[58:61], v[138:141], v[206:209], v[58:61]
	s_barrier
	v_mfma_f32_16x16x32_bf16 v[50:53], v[130:133], v[214:217], v[50:53]
	v_mfma_f32_16x16x32_bf16 v[42:45], v[138:141], v[214:217], v[42:45]
	v_mfma_f32_16x16x32_bf16 v[34:37], v[130:133], v[222:225], v[34:37]
	v_mfma_f32_16x16x32_bf16 v[26:29], v[138:141], v[222:225], v[26:29]
	v_mfma_f32_16x16x32_bf16 v[18:21], v[130:133], v[230:233], v[18:21]
	v_mfma_f32_16x16x32_bf16 v[10:13], v[138:141], v[230:233], v[10:13]
	v_mfma_f32_16x16x32_bf16 v[62:65], v[134:137], v[210:213], v[62:65]
	v_mfma_f32_16x16x32_bf16 v[58:61], v[142:145], v[210:213], v[58:61]
	v_mfma_f32_16x16x32_bf16 v[50:53], v[134:137], v[218:221], v[50:53]
	v_mfma_f32_16x16x32_bf16 v[42:45], v[142:145], v[218:221], v[42:45]
	v_mfma_f32_16x16x32_bf16 v[34:37], v[134:137], v[226:229], v[34:37]
	v_mfma_f32_16x16x32_bf16 v[26:29], v[142:145], v[226:229], v[26:29]
	v_mfma_f32_16x16x32_bf16 v[18:21], v[134:137], v[234:237], v[18:21]
	v_mfma_f32_16x16x32_bf16 v[10:13], v[142:145], v[234:237], v[10:13]
	v_mfma_f32_16x16x32_bf16 v[54:57], v[146:149], v[206:209], v[54:57]
	v_mfma_f32_16x16x32_bf16 v[46:49], v[178:181], v[206:209], v[46:49]
	v_mfma_f32_16x16x32_bf16 v[38:41], v[146:149], v[214:217], v[38:41]
	v_mfma_f32_16x16x32_bf16 v[30:33], v[178:181], v[214:217], v[30:33]
	v_mfma_f32_16x16x32_bf16 v[22:25], v[146:149], v[222:225], v[22:25]
	v_mfma_f32_16x16x32_bf16 v[14:17], v[178:181], v[222:225], v[14:17]
	v_mfma_f32_16x16x32_bf16 v[6:9], v[146:149], v[230:233], v[6:9]
	v_mfma_f32_16x16x32_bf16 v[2:5], v[178:181], v[230:233], v[2:5]
	v_mfma_f32_16x16x32_bf16 v[54:57], v[160:163], v[210:213], v[54:57]
	v_mfma_f32_16x16x32_bf16 v[46:49], v[182:185], v[210:213], v[46:49]
	v_mfma_f32_16x16x32_bf16 v[38:41], v[160:163], v[218:221], v[38:41]
	v_mfma_f32_16x16x32_bf16 v[30:33], v[182:185], v[218:221], v[30:33]
	v_mfma_f32_16x16x32_bf16 v[22:25], v[160:163], v[226:229], v[22:25]
	v_mfma_f32_16x16x32_bf16 v[14:17], v[182:185], v[226:229], v[14:17]
	v_mfma_f32_16x16x32_bf16 v[6:9], v[160:163], v[234:237], v[6:9]
	v_mfma_f32_16x16x32_bf16 v[2:5], v[182:185], v[234:237], v[2:5]
	s_barrier
	s_setprio 0
	s_add_i32 s48, 0, 0x18000
	s_add_i32 s49, 0, 0x1c000
	v_add_u32_e32 v142, s48, v186
	v_add_u32_e32 v182, s49, v186
	ds_read_b128 v[130:133], v142
	ds_read_b128 v[134:137], v142 offset:1024
	ds_read_b128 v[138:141], v142 offset:2048
	ds_read_b128 v[142:145], v142 offset:3072
	ds_read_b128 v[146:149], v182
	ds_read_b128 v[160:163], v182 offset:1024
	ds_read_b128 v[178:181], v182 offset:2048
	ds_read_b128 v[182:185], v182 offset:3072
	s_add_u32 s46, s64, 0x200000
	s_addc_u32 s47, s65, 0
	s_mov_b32 m0, s73
	v_lshl_add_u64 v[248:249], s[46:47], 0, v[150:151]
	ds_read_b128 v[206:209], v188 offset:32768
	ds_read_b128 v[210:213], v188 offset:33792
	ds_read_b128 v[214:217], v188 offset:34816
	ds_read_b128 v[218:221], v188 offset:35840
	ds_read_b128 v[222:225], v188 offset:36864
	ds_read_b128 v[226:229], v188 offset:37888
	ds_read_b128 v[230:233], v188 offset:38912
	ds_read_b128 v[234:237], v188 offset:39936
	global_load_lds_dwordx4 v[248:249], off
	v_lshl_add_u64 v[248:249], s[46:47], 0, v[152:153]
	s_mov_b32 m0, s74
	s_nop 0
	global_load_lds_dwordx4 v[248:249], off
	s_waitcnt vmcnt(8)
	s_waitcnt lgkmcnt(0)
	s_setprio 1
	s_waitcnt lgkmcnt(0)
	v_mfma_f32_16x16x32_bf16 v[126:129], v[130:133], v[206:209], v[126:129]
	v_mfma_f32_16x16x32_bf16 v[122:125], v[138:141], v[206:209], v[122:125]
	v_mfma_f32_16x16x32_bf16 v[118:121], v[130:133], v[214:217], v[118:121]
	v_mfma_f32_16x16x32_bf16 v[110:113], v[138:141], v[214:217], v[110:113]
	s_barrier
	v_mfma_f32_16x16x32_bf16 v[94:97], v[130:133], v[222:225], v[94:97]
	v_mfma_f32_16x16x32_bf16 v[90:93], v[138:141], v[222:225], v[90:93]
	v_mfma_f32_16x16x32_bf16 v[82:85], v[130:133], v[230:233], v[82:85]
	v_mfma_f32_16x16x32_bf16 v[74:77], v[138:141], v[230:233], v[74:77]
	v_mfma_f32_16x16x32_bf16 v[126:129], v[134:137], v[210:213], v[126:129]
	v_mfma_f32_16x16x32_bf16 v[122:125], v[142:145], v[210:213], v[122:125]
	v_mfma_f32_16x16x32_bf16 v[118:121], v[134:137], v[218:221], v[118:121]
	v_mfma_f32_16x16x32_bf16 v[110:113], v[142:145], v[218:221], v[110:113]
	v_mfma_f32_16x16x32_bf16 v[94:97], v[134:137], v[226:229], v[94:97]
	v_mfma_f32_16x16x32_bf16 v[90:93], v[142:145], v[226:229], v[90:93]
	v_mfma_f32_16x16x32_bf16 v[82:85], v[134:137], v[234:237], v[82:85]
	v_mfma_f32_16x16x32_bf16 v[74:77], v[142:145], v[234:237], v[74:77]
	v_mfma_f32_16x16x32_bf16 v[114:117], v[146:149], v[206:209], v[114:117]
	v_mfma_f32_16x16x32_bf16 v[106:109], v[178:181], v[206:209], v[106:109]
	v_mfma_f32_16x16x32_bf16 v[102:105], v[146:149], v[214:217], v[102:105]
	v_mfma_f32_16x16x32_bf16 v[98:101], v[178:181], v[214:217], v[98:101]
	v_mfma_f32_16x16x32_bf16 v[86:89], v[146:149], v[222:225], v[86:89]
	v_mfma_f32_16x16x32_bf16 v[78:81], v[178:181], v[222:225], v[78:81]
	v_mfma_f32_16x16x32_bf16 v[70:73], v[146:149], v[230:233], v[70:73]
	v_mfma_f32_16x16x32_bf16 v[66:69], v[178:181], v[230:233], v[66:69]
	v_mfma_f32_16x16x32_bf16 v[114:117], v[160:163], v[210:213], v[114:117]
	v_mfma_f32_16x16x32_bf16 v[106:109], v[182:185], v[210:213], v[106:109]
	v_mfma_f32_16x16x32_bf16 v[102:105], v[160:163], v[218:221], v[102:105]
	v_mfma_f32_16x16x32_bf16 v[98:101], v[182:185], v[218:221], v[98:101]
	v_mfma_f32_16x16x32_bf16 v[86:89], v[160:163], v[226:229], v[86:89]
	v_mfma_f32_16x16x32_bf16 v[78:81], v[182:185], v[226:229], v[78:81]
	v_mfma_f32_16x16x32_bf16 v[70:73], v[160:163], v[234:237], v[70:73]
	v_mfma_f32_16x16x32_bf16 v[66:69], v[182:185], v[234:237], v[66:69]
	s_barrier
	s_setprio 0
	s_add_i32 s46, s48, s70
	v_lshl_add_u64 v[164:165], v[164:165], 0, s[42:43]
	s_mov_b32 m0, s46
	ds_read_b128 v[206:209], v188 offset:49152
	ds_read_b128 v[210:213], v188 offset:50176
	ds_read_b128 v[214:217], v188 offset:51200
	ds_read_b128 v[218:221], v188 offset:52224
	ds_read_b128 v[222:225], v188 offset:53248
	ds_read_b128 v[226:229], v188 offset:54272
	ds_read_b128 v[230:233], v188 offset:55296
	ds_read_b128 v[234:237], v188 offset:56320
	global_load_lds_dwordx4 v[164:165], off
	s_add_i32 m0, s46, 0x2000
	s_add_u32 s46, s60, 0x200080
	v_lshl_add_u64 v[164:165], v[242:243], 0, s[42:43]
	s_addc_u32 s47, s61, 0
	s_add_i32 s48, s49, s70
	global_load_lds_dwordx4 v[164:165], off
	v_lshl_add_u64 v[164:165], s[46:47], 0, v[166:167]
	s_mov_b32 m0, s48
	s_nop 0
	global_load_lds_dwordx4 v[164:165], off
	v_lshl_add_u64 v[164:165], s[46:47], 0, v[154:155]
	s_add_i32 m0, s48, 0x2000
	s_nop 0
	global_load_lds_dwordx4 v[164:165], off
	v_lshl_add_u64 v[164:165], v[244:245], 0, s[42:43]
	s_mov_b32 m0, s75
	s_nop 0
	global_load_lds_dwordx4 v[164:165], off
	v_lshl_add_u64 v[164:165], v[246:247], 0, s[42:43]
	s_mov_b32 m0, s76
	s_nop 0
	global_load_lds_dwordx4 v[164:165], off
	s_waitcnt vmcnt(8)
	s_waitcnt lgkmcnt(0)
	s_setprio 1
	s_waitcnt lgkmcnt(0)
	v_mfma_f32_16x16x32_bf16 v[62:65], v[130:133], v[206:209], v[62:65]
	v_mfma_f32_16x16x32_bf16 v[58:61], v[138:141], v[206:209], v[58:61]
	s_barrier
	v_mfma_f32_16x16x32_bf16 v[50:53], v[130:133], v[214:217], v[50:53]
	v_mfma_f32_16x16x32_bf16 v[42:45], v[138:141], v[214:217], v[42:45]
	v_mfma_f32_16x16x32_bf16 v[34:37], v[130:133], v[222:225], v[34:37]
	v_mfma_f32_16x16x32_bf16 v[26:29], v[138:141], v[222:225], v[26:29]
	v_mfma_f32_16x16x32_bf16 v[18:21], v[130:133], v[230:233], v[18:21]
	v_mfma_f32_16x16x32_bf16 v[10:13], v[138:141], v[230:233], v[10:13]
	v_mfma_f32_16x16x32_bf16 v[62:65], v[134:137], v[210:213], v[62:65]
	v_mfma_f32_16x16x32_bf16 v[58:61], v[142:145], v[210:213], v[58:61]
	v_mfma_f32_16x16x32_bf16 v[50:53], v[134:137], v[218:221], v[50:53]
	v_mfma_f32_16x16x32_bf16 v[42:45], v[142:145], v[218:221], v[42:45]
	v_mfma_f32_16x16x32_bf16 v[34:37], v[134:137], v[226:229], v[34:37]
	v_mfma_f32_16x16x32_bf16 v[26:29], v[142:145], v[226:229], v[26:29]
	v_mfma_f32_16x16x32_bf16 v[18:21], v[134:137], v[234:237], v[18:21]
	v_mfma_f32_16x16x32_bf16 v[10:13], v[142:145], v[234:237], v[10:13]
	v_mfma_f32_16x16x32_bf16 v[54:57], v[146:149], v[206:209], v[54:57]
	v_mfma_f32_16x16x32_bf16 v[46:49], v[178:181], v[206:209], v[46:49]
	v_mfma_f32_16x16x32_bf16 v[38:41], v[146:149], v[214:217], v[38:41]
	v_mfma_f32_16x16x32_bf16 v[30:33], v[178:181], v[214:217], v[30:33]
	v_mfma_f32_16x16x32_bf16 v[22:25], v[146:149], v[222:225], v[22:25]
	v_mfma_f32_16x16x32_bf16 v[14:17], v[178:181], v[222:225], v[14:17]
	v_mfma_f32_16x16x32_bf16 v[6:9], v[146:149], v[230:233], v[6:9]
	v_mfma_f32_16x16x32_bf16 v[2:5], v[178:181], v[230:233], v[2:5]
	v_mfma_f32_16x16x32_bf16 v[54:57], v[160:163], v[210:213], v[54:57]
	v_mfma_f32_16x16x32_bf16 v[46:49], v[182:185], v[210:213], v[46:49]
	v_mfma_f32_16x16x32_bf16 v[38:41], v[160:163], v[218:221], v[38:41]
	v_mfma_f32_16x16x32_bf16 v[30:33], v[182:185], v[218:221], v[30:33]
	v_mfma_f32_16x16x32_bf16 v[22:25], v[160:163], v[226:229], v[22:25]
	v_mfma_f32_16x16x32_bf16 v[14:17], v[182:185], v[226:229], v[14:17]
	v_mfma_f32_16x16x32_bf16 v[6:9], v[160:163], v[234:237], v[6:9]
	v_mfma_f32_16x16x32_bf16 v[2:5], v[182:185], v[234:237], v[2:5]
	s_barrier
	s_setprio 0
	s_add_i32 s82, s82, 2
	s_add_u32 s62, s62, 0x100
	s_addc_u32 s63, s63, 0
	s_add_u32 s80, s80, 0x100
	s_addc_u32 s81, s81, 0
	s_cmpk_gt_u32 s82, 0x7d
	s_cbranch_scc0 .LBB0_1138
	s_and_b64 vcc, exec, s[10:11]
	s_cbranch_vccz .LBB0_1141
	s_barrier
